# GEMM K-loops: 48 LDS-DMA loads switched to saddr form (scalar base + per-lane 32-bit offset), dropping a 64-bit VALU add per load
# speedup vs baseline: 1.0024x; 1.0024x over previous
.LBB0_253:
	s_add_u32 s26, s0, 0xfffc0080
	s_addc_u32 s27, s1, -1
	s_add_i32 s55, 0, 0x10000
	s_cmp_eq_u32 s54, 12
	s_cselect_b32 s31, s19, s27
	s_cselect_b32 s30, s50, s26
	v_add_u32_e32 v138, s55, v141
	s_cselect_b32 s27, s11, s53
	s_cselect_b32 s26, s51, s52
	s_add_i32 s58, 0, 0x14000
	ds_read_b128 v[144:147], v138
	ds_read_b128 v[158:161], v138 offset:1024
	ds_read_b128 v[162:165], v138 offset:2048
	ds_read_b128 v[166:169], v138 offset:3072
	v_add_u32_e32 v138, s58, v141
	ds_read_b128 v[170:173], v138
	ds_read_b128 v[174:177], v138 offset:1024
	ds_read_b128 v[178:181], v138 offset:2048
	ds_read_b128 v[182:185], v138 offset:3072
	s_add_i32 m0, s38, 0xc000
	ds_read_b128 v[186:189], v143
	ds_read_b128 v[190:193], v143 offset:1024
	ds_read_b128 v[194:197], v143 offset:2048
	ds_read_b128 v[198:201], v143 offset:3072
	ds_read_b128 v[202:205], v143 offset:4096
	ds_read_b128 v[218:221], v143 offset:5120
	ds_read_b128 v[222:225], v143 offset:6144
	ds_read_b128 v[226:229], v143 offset:7168
	global_load_lds_dwordx4 v134, s[0:1]
	s_add_i32 m0, s38, 0xe000
	s_nop 0
	global_load_lds_dwordx4 v136, s[0:1]
	s_cmp_lg_u32 s54, -2
	s_cbranch_scc1 .Lz_skip_0
	v_mov_b64_e32 v[0:1], 0
	v_mov_b64_e32 v[2:3], 0
	v_mov_b64_e32 v[8:9], 0
	v_mov_b64_e32 v[10:11], 0
	v_mov_b64_e32 v[16:17], 0
	v_mov_b64_e32 v[18:19], 0
	v_mov_b64_e32 v[24:25], 0
	v_mov_b64_e32 v[26:27], 0
	v_mov_b64_e32 v[32:33], 0
	v_mov_b64_e32 v[34:35], 0
	v_mov_b64_e32 v[40:41], 0
	v_mov_b64_e32 v[42:43], 0
	v_mov_b64_e32 v[48:49], 0
	v_mov_b64_e32 v[50:51], 0
	v_mov_b64_e32 v[56:57], 0
	v_mov_b64_e32 v[58:59], 0
	v_mov_b64_e32 v[4:5], 0
	v_mov_b64_e32 v[6:7], 0
	v_mov_b64_e32 v[12:13], 0
	v_mov_b64_e32 v[14:15], 0
	v_mov_b64_e32 v[20:21], 0
	v_mov_b64_e32 v[22:23], 0
	v_mov_b64_e32 v[28:29], 0
	v_mov_b64_e32 v[30:31], 0
	v_mov_b64_e32 v[36:37], 0
	v_mov_b64_e32 v[38:39], 0
	v_mov_b64_e32 v[44:45], 0
	v_mov_b64_e32 v[46:47], 0
	v_mov_b64_e32 v[52:53], 0
	v_mov_b64_e32 v[54:55], 0
	v_mov_b64_e32 v[60:61], 0
	v_mov_b64_e32 v[62:63], 0
	v_mov_b64_e32 v[64:65], 0
	v_mov_b64_e32 v[66:67], 0
	v_mov_b64_e32 v[72:73], 0
	v_mov_b64_e32 v[74:75], 0
	v_mov_b64_e32 v[80:81], 0
	v_mov_b64_e32 v[82:83], 0
	v_mov_b64_e32 v[88:89], 0
	v_mov_b64_e32 v[90:91], 0
	v_mov_b64_e32 v[96:97], 0
	v_mov_b64_e32 v[98:99], 0
	v_mov_b64_e32 v[104:105], 0
	v_mov_b64_e32 v[106:107], 0
	v_mov_b64_e32 v[112:113], 0
	v_mov_b64_e32 v[114:115], 0
	v_mov_b64_e32 v[120:121], 0
	v_mov_b64_e32 v[122:123], 0
	v_mov_b64_e32 v[68:69], 0
	v_mov_b64_e32 v[70:71], 0
	v_mov_b64_e32 v[76:77], 0
	v_mov_b64_e32 v[78:79], 0
	v_mov_b64_e32 v[84:85], 0
	v_mov_b64_e32 v[86:87], 0
	v_mov_b64_e32 v[92:93], 0
	v_mov_b64_e32 v[94:95], 0
	v_mov_b64_e32 v[100:101], 0
	v_mov_b64_e32 v[102:103], 0
	v_mov_b64_e32 v[108:109], 0
	v_mov_b64_e32 v[110:111], 0
	v_mov_b64_e32 v[116:117], 0
	v_mov_b64_e32 v[118:119], 0
	v_mov_b64_e32 v[124:125], 0
	v_mov_b64_e32 v[126:127], 0
.Lz_skip_0:
	s_waitcnt vmcnt(8)
	s_waitcnt lgkmcnt(0)
	s_barrier
	s_waitcnt lgkmcnt(0)
	v_mfma_f32_16x16x32_bf16 v[124:127], v[144:147], v[186:189], v[124:127]
	v_mfma_f32_16x16x32_bf16 v[116:119], v[162:165], v[186:189], v[116:119]
	v_mfma_f32_16x16x32_bf16 v[108:111], v[144:147], v[194:197], v[108:111]
	v_mfma_f32_16x16x32_bf16 v[100:103], v[162:165], v[194:197], v[100:103]
	v_mfma_f32_16x16x32_bf16 v[92:95], v[144:147], v[202:205], v[92:95]
	v_mfma_f32_16x16x32_bf16 v[84:87], v[162:165], v[202:205], v[84:87]
	v_mfma_f32_16x16x32_bf16 v[76:79], v[144:147], v[222:225], v[76:79]
	v_mfma_f32_16x16x32_bf16 v[68:71], v[162:165], v[222:225], v[68:71]
	v_mfma_f32_16x16x32_bf16 v[124:127], v[158:161], v[190:193], v[124:127]
	v_mfma_f32_16x16x32_bf16 v[116:119], v[166:169], v[190:193], v[116:119]
	v_mfma_f32_16x16x32_bf16 v[108:111], v[158:161], v[198:201], v[108:111]
	v_mfma_f32_16x16x32_bf16 v[100:103], v[166:169], v[198:201], v[100:103]
	v_mfma_f32_16x16x32_bf16 v[92:95], v[158:161], v[218:221], v[92:95]
	v_mfma_f32_16x16x32_bf16 v[84:87], v[166:169], v[218:221], v[84:87]
	v_mfma_f32_16x16x32_bf16 v[76:79], v[158:161], v[226:229], v[76:79]
	v_mfma_f32_16x16x32_bf16 v[68:71], v[166:169], v[226:229], v[68:71]
	v_mfma_f32_16x16x32_bf16 v[120:123], v[170:173], v[186:189], v[120:123]
	v_mfma_f32_16x16x32_bf16 v[112:115], v[178:181], v[186:189], v[112:115]
	v_mfma_f32_16x16x32_bf16 v[104:107], v[170:173], v[194:197], v[104:107]
	v_mfma_f32_16x16x32_bf16 v[96:99], v[178:181], v[194:197], v[96:99]
	v_mfma_f32_16x16x32_bf16 v[88:91], v[170:173], v[202:205], v[88:91]
	v_mfma_f32_16x16x32_bf16 v[80:83], v[178:181], v[202:205], v[80:83]
	v_mfma_f32_16x16x32_bf16 v[72:75], v[170:173], v[222:225], v[72:75]
	v_mfma_f32_16x16x32_bf16 v[64:67], v[178:181], v[222:225], v[64:67]
	v_mfma_f32_16x16x32_bf16 v[120:123], v[174:177], v[190:193], v[120:123]
	v_mfma_f32_16x16x32_bf16 v[112:115], v[182:185], v[190:193], v[112:115]
	v_mfma_f32_16x16x32_bf16 v[104:107], v[174:177], v[198:201], v[104:107]
	v_mfma_f32_16x16x32_bf16 v[96:99], v[182:185], v[198:201], v[96:99]
	v_mfma_f32_16x16x32_bf16 v[88:91], v[174:177], v[218:221], v[88:91]
	v_mfma_f32_16x16x32_bf16 v[80:83], v[182:185], v[218:221], v[80:83]
	v_mfma_f32_16x16x32_bf16 v[72:75], v[174:177], v[226:229], v[72:75]
	v_mfma_f32_16x16x32_bf16 v[64:67], v[182:185], v[226:229], v[64:67]
	s_barrier
	s_add_i32 s55, s55, s37
	v_lshl_add_u64 v[138:139], s[26:27], 0, v[148:149]
	s_mov_b32 m0, s55
	ds_read_b128 v[186:189], v143 offset:16384
	ds_read_b128 v[190:193], v143 offset:17408
	ds_read_b128 v[194:197], v143 offset:18432
	ds_read_b128 v[198:201], v143 offset:19456
	ds_read_b128 v[202:205], v143 offset:20480
	ds_read_b128 v[218:221], v143 offset:21504
	ds_read_b128 v[222:225], v143 offset:22528
	ds_read_b128 v[226:229], v143 offset:23552
	global_load_lds_dwordx4 v[138:139], off
	s_add_i32 m0, s55, 0x2000
	s_add_u32 s56, s26, 0x40000
	v_lshl_add_u64 v[154:155], s[26:27], 0, v[128:129]
	s_addc_u32 s57, s27, 0
	s_add_i32 s55, s58, s37
	global_load_lds_dwordx4 v[154:155], off
	s_mov_b32 m0, s55
	v_lshl_add_u64 v[212:213], s[30:31], 0, v[130:131]
	global_load_lds_dwordx4 v148, s[56:57]
	s_add_i32 m0, s55, 0x2000
	s_nop 0
	global_load_lds_dwordx4 v128, s[56:57]
	v_lshl_add_u64 v[156:157], s[30:31], 0, v[132:133]
	s_mov_b32 m0, s38
	s_nop 0
	global_load_lds_dwordx4 v[156:157], off
	s_mov_b32 m0, s39
	s_nop 0
	global_load_lds_dwordx4 v[212:213], off
	s_waitcnt vmcnt(8)
	s_waitcnt lgkmcnt(0)
	s_barrier
	s_waitcnt lgkmcnt(0)
	v_mfma_f32_16x16x32_bf16 v[60:63], v[144:147], v[186:189], v[60:63]
	v_mfma_f32_16x16x32_bf16 v[52:55], v[162:165], v[186:189], v[52:55]
	v_mfma_f32_16x16x32_bf16 v[44:47], v[144:147], v[194:197], v[44:47]
	v_mfma_f32_16x16x32_bf16 v[36:39], v[162:165], v[194:197], v[36:39]
	v_mfma_f32_16x16x32_bf16 v[28:31], v[144:147], v[202:205], v[28:31]
	v_mfma_f32_16x16x32_bf16 v[20:23], v[162:165], v[202:205], v[20:23]
	v_mfma_f32_16x16x32_bf16 v[12:15], v[144:147], v[222:225], v[12:15]
	v_mfma_f32_16x16x32_bf16 v[4:7], v[162:165], v[222:225], v[4:7]
	v_mfma_f32_16x16x32_bf16 v[60:63], v[158:161], v[190:193], v[60:63]
	v_mfma_f32_16x16x32_bf16 v[52:55], v[166:169], v[190:193], v[52:55]
	v_mfma_f32_16x16x32_bf16 v[44:47], v[158:161], v[198:201], v[44:47]
	v_mfma_f32_16x16x32_bf16 v[36:39], v[166:169], v[198:201], v[36:39]
	v_mfma_f32_16x16x32_bf16 v[28:31], v[158:161], v[218:221], v[28:31]
	v_mfma_f32_16x16x32_bf16 v[20:23], v[166:169], v[218:221], v[20:23]
	v_mfma_f32_16x16x32_bf16 v[12:15], v[158:161], v[226:229], v[12:15]
	v_mfma_f32_16x16x32_bf16 v[4:7], v[166:169], v[226:229], v[4:7]
	v_mfma_f32_16x16x32_bf16 v[56:59], v[170:173], v[186:189], v[56:59]
	v_mfma_f32_16x16x32_bf16 v[48:51], v[178:181], v[186:189], v[48:51]
	v_mfma_f32_16x16x32_bf16 v[40:43], v[170:173], v[194:197], v[40:43]
	v_mfma_f32_16x16x32_bf16 v[32:35], v[178:181], v[194:197], v[32:35]
	v_mfma_f32_16x16x32_bf16 v[24:27], v[170:173], v[202:205], v[24:27]
	v_mfma_f32_16x16x32_bf16 v[16:19], v[178:181], v[202:205], v[16:19]
	v_mfma_f32_16x16x32_bf16 v[8:11], v[170:173], v[222:225], v[8:11]
	v_mfma_f32_16x16x32_bf16 v[0:3], v[178:181], v[222:225], v[0:3]
	v_mfma_f32_16x16x32_bf16 v[56:59], v[174:177], v[190:193], v[56:59]
	v_mfma_f32_16x16x32_bf16 v[48:51], v[182:185], v[190:193], v[48:51]
	v_mfma_f32_16x16x32_bf16 v[40:43], v[174:177], v[198:201], v[40:43]
	v_mfma_f32_16x16x32_bf16 v[32:35], v[182:185], v[198:201], v[32:35]
	v_mfma_f32_16x16x32_bf16 v[24:27], v[174:177], v[218:221], v[24:27]
	v_mfma_f32_16x16x32_bf16 v[16:19], v[182:185], v[218:221], v[16:19]
	v_mfma_f32_16x16x32_bf16 v[8:11], v[174:177], v[226:229], v[8:11]
	v_mfma_f32_16x16x32_bf16 v[0:3], v[182:185], v[226:229], v[0:3]
	s_barrier
	s_add_i32 s55, 0, 0x18000
	v_add_u32_e32 v140, s55, v141
	s_add_i32 s56, 0, 0x1c000
	ds_read_b128 v[144:147], v140
	ds_read_b128 v[158:161], v140 offset:1024
	ds_read_b128 v[162:165], v140 offset:2048
	ds_read_b128 v[166:169], v140 offset:3072
	v_add_u32_e32 v140, s56, v141
	ds_read_b128 v[170:173], v140
	ds_read_b128 v[174:177], v140 offset:1024
	ds_read_b128 v[178:181], v140 offset:2048
	ds_read_b128 v[182:185], v140 offset:3072
	s_add_u32 s30, s30, 0x40000
	s_addc_u32 s31, s31, 0
	s_mov_b32 m0, s40
	ds_read_b128 v[186:189], v143 offset:32768
	ds_read_b128 v[190:193], v143 offset:33792
	ds_read_b128 v[194:197], v143 offset:34816
	ds_read_b128 v[198:201], v143 offset:35840
	ds_read_b128 v[202:205], v143 offset:36864
	ds_read_b128 v[218:221], v143 offset:37888
	ds_read_b128 v[222:225], v143 offset:38912
	ds_read_b128 v[226:229], v143 offset:39936
	global_load_lds_dwordx4 v132, s[30:31]
	s_mov_b32 m0, s41
	s_nop 0
	global_load_lds_dwordx4 v130, s[30:31]
	s_waitcnt vmcnt(8)
	s_waitcnt lgkmcnt(0)
	s_barrier
	s_waitcnt lgkmcnt(0)
	v_mfma_f32_16x16x32_bf16 v[124:127], v[144:147], v[186:189], v[124:127]
	v_mfma_f32_16x16x32_bf16 v[116:119], v[162:165], v[186:189], v[116:119]
	v_mfma_f32_16x16x32_bf16 v[108:111], v[144:147], v[194:197], v[108:111]
	v_mfma_f32_16x16x32_bf16 v[100:103], v[162:165], v[194:197], v[100:103]
	v_mfma_f32_16x16x32_bf16 v[92:95], v[144:147], v[202:205], v[92:95]
	v_mfma_f32_16x16x32_bf16 v[84:87], v[162:165], v[202:205], v[84:87]
	v_mfma_f32_16x16x32_bf16 v[76:79], v[144:147], v[222:225], v[76:79]
	v_mfma_f32_16x16x32_bf16 v[68:71], v[162:165], v[222:225], v[68:71]
	v_mfma_f32_16x16x32_bf16 v[124:127], v[158:161], v[190:193], v[124:127]
	v_mfma_f32_16x16x32_bf16 v[116:119], v[166:169], v[190:193], v[116:119]
	v_mfma_f32_16x16x32_bf16 v[108:111], v[158:161], v[198:201], v[108:111]
	v_mfma_f32_16x16x32_bf16 v[100:103], v[166:169], v[198:201], v[100:103]
	v_mfma_f32_16x16x32_bf16 v[92:95], v[158:161], v[218:221], v[92:95]
	v_mfma_f32_16x16x32_bf16 v[84:87], v[166:169], v[218:221], v[84:87]
	v_mfma_f32_16x16x32_bf16 v[76:79], v[158:161], v[226:229], v[76:79]
	v_mfma_f32_16x16x32_bf16 v[68:71], v[166:169], v[226:229], v[68:71]
	v_mfma_f32_16x16x32_bf16 v[120:123], v[170:173], v[186:189], v[120:123]
	v_mfma_f32_16x16x32_bf16 v[112:115], v[178:181], v[186:189], v[112:115]
	v_mfma_f32_16x16x32_bf16 v[104:107], v[170:173], v[194:197], v[104:107]
	v_mfma_f32_16x16x32_bf16 v[96:99], v[178:181], v[194:197], v[96:99]
	v_mfma_f32_16x16x32_bf16 v[88:91], v[170:173], v[202:205], v[88:91]
	v_mfma_f32_16x16x32_bf16 v[80:83], v[178:181], v[202:205], v[80:83]
	v_mfma_f32_16x16x32_bf16 v[72:75], v[170:173], v[222:225], v[72:75]
	v_mfma_f32_16x16x32_bf16 v[64:67], v[178:181], v[222:225], v[64:67]
	v_mfma_f32_16x16x32_bf16 v[120:123], v[174:177], v[190:193], v[120:123]
	v_mfma_f32_16x16x32_bf16 v[112:115], v[182:185], v[190:193], v[112:115]
	v_mfma_f32_16x16x32_bf16 v[104:107], v[174:177], v[198:201], v[104:107]
	v_mfma_f32_16x16x32_bf16 v[96:99], v[182:185], v[198:201], v[96:99]
	v_mfma_f32_16x16x32_bf16 v[88:91], v[174:177], v[218:221], v[88:91]
	v_mfma_f32_16x16x32_bf16 v[80:83], v[182:185], v[218:221], v[80:83]
	v_mfma_f32_16x16x32_bf16 v[72:75], v[174:177], v[226:229], v[72:75]
	v_mfma_f32_16x16x32_bf16 v[64:67], v[182:185], v[226:229], v[64:67]
	s_barrier
	s_add_i32 s30, s55, s37
	v_lshl_add_u64 v[138:139], v[138:139], 0, s[28:29]
	s_mov_b32 m0, s30
	ds_read_b128 v[186:189], v143 offset:49152
	ds_read_b128 v[190:193], v143 offset:50176
	ds_read_b128 v[194:197], v143 offset:51200
	ds_read_b128 v[198:201], v143 offset:52224
	ds_read_b128 v[202:205], v143 offset:53248
	ds_read_b128 v[218:221], v143 offset:54272
	ds_read_b128 v[222:225], v143 offset:55296
	ds_read_b128 v[226:229], v143 offset:56320
	global_load_lds_dwordx4 v[138:139], off
	s_add_i32 m0, s30, 0x2000
	s_add_u32 s26, s26, 0x40080
	v_lshl_add_u64 v[138:139], v[154:155], 0, s[28:29]
	s_addc_u32 s27, s27, 0
	s_add_i32 s30, s56, s37
	global_load_lds_dwordx4 v[138:139], off
	s_mov_b32 m0, s30
	s_nop 0
	global_load_lds_dwordx4 v148, s[26:27]
	s_add_i32 m0, s30, 0x2000
	s_nop 0
	global_load_lds_dwordx4 v128, s[26:27]
	v_lshl_add_u64 v[138:139], v[156:157], 0, s[28:29]
	s_mov_b32 m0, s46
	s_nop 0
	global_load_lds_dwordx4 v[138:139], off
	v_lshl_add_u64 v[138:139], v[212:213], 0, s[28:29]
	s_mov_b32 m0, s47
	s_nop 0
	global_load_lds_dwordx4 v[138:139], off
	s_waitcnt vmcnt(8)
	s_waitcnt lgkmcnt(0)
	s_barrier
	s_waitcnt lgkmcnt(0)
	v_mfma_f32_16x16x32_bf16 v[60:63], v[144:147], v[186:189], v[60:63]
	v_mfma_f32_16x16x32_bf16 v[52:55], v[162:165], v[186:189], v[52:55]
	v_mfma_f32_16x16x32_bf16 v[44:47], v[144:147], v[194:197], v[44:47]
	v_mfma_f32_16x16x32_bf16 v[36:39], v[162:165], v[194:197], v[36:39]
	v_mfma_f32_16x16x32_bf16 v[28:31], v[144:147], v[202:205], v[28:31]
	v_mfma_f32_16x16x32_bf16 v[20:23], v[162:165], v[202:205], v[20:23]
	v_mfma_f32_16x16x32_bf16 v[12:15], v[144:147], v[222:225], v[12:15]
	v_mfma_f32_16x16x32_bf16 v[4:7], v[162:165], v[222:225], v[4:7]
	v_mfma_f32_16x16x32_bf16 v[60:63], v[158:161], v[190:193], v[60:63]
	v_mfma_f32_16x16x32_bf16 v[52:55], v[166:169], v[190:193], v[52:55]
	v_mfma_f32_16x16x32_bf16 v[44:47], v[158:161], v[198:201], v[44:47]
	v_mfma_f32_16x16x32_bf16 v[36:39], v[166:169], v[198:201], v[36:39]
	v_mfma_f32_16x16x32_bf16 v[28:31], v[158:161], v[218:221], v[28:31]
	v_mfma_f32_16x16x32_bf16 v[20:23], v[166:169], v[218:221], v[20:23]
	v_mfma_f32_16x16x32_bf16 v[12:15], v[158:161], v[226:229], v[12:15]
	v_mfma_f32_16x16x32_bf16 v[4:7], v[166:169], v[226:229], v[4:7]
	v_mfma_f32_16x16x32_bf16 v[56:59], v[170:173], v[186:189], v[56:59]
	v_mfma_f32_16x16x32_bf16 v[48:51], v[178:181], v[186:189], v[48:51]
	v_mfma_f32_16x16x32_bf16 v[40:43], v[170:173], v[194:197], v[40:43]
	v_mfma_f32_16x16x32_bf16 v[32:35], v[178:181], v[194:197], v[32:35]
	v_mfma_f32_16x16x32_bf16 v[24:27], v[170:173], v[202:205], v[24:27]
	v_mfma_f32_16x16x32_bf16 v[16:19], v[178:181], v[202:205], v[16:19]
	v_mfma_f32_16x16x32_bf16 v[8:11], v[170:173], v[222:225], v[8:11]
	v_mfma_f32_16x16x32_bf16 v[0:3], v[178:181], v[222:225], v[0:3]
	v_mfma_f32_16x16x32_bf16 v[56:59], v[174:177], v[190:193], v[56:59]
	v_mfma_f32_16x16x32_bf16 v[48:51], v[182:185], v[190:193], v[48:51]
	v_mfma_f32_16x16x32_bf16 v[40:43], v[174:177], v[198:201], v[40:43]
	v_mfma_f32_16x16x32_bf16 v[32:35], v[182:185], v[198:201], v[32:35]
	v_mfma_f32_16x16x32_bf16 v[24:27], v[174:177], v[218:221], v[24:27]
	v_mfma_f32_16x16x32_bf16 v[16:19], v[182:185], v[218:221], v[16:19]
	v_mfma_f32_16x16x32_bf16 v[8:11], v[174:177], v[226:229], v[8:11]
	v_mfma_f32_16x16x32_bf16 v[0:3], v[182:185], v[226:229], v[0:3]
	s_barrier
	s_add_i32 s54, s54, 2
	s_add_u32 s0, s0, 0x100
	s_addc_u32 s1, s1, 0
	s_add_u32 s52, s52, 0x100
	s_addc_u32 s53, s53, 0
	s_cmp_gt_u32 s54, 13
	s_cbranch_scc0 .LBB0_253
	s_and_b64 vcc, exec, s[8:9]
	s_cbranch_vccz .LBB0_256
	s_barrier

.LBB0_360:
	s_add_u32 s0, s4, 0x100
	s_addc_u32 s1, s5, 0
	s_add_i32 s45, 0, 0x10000
	s_cmp_eq_u32 s44, 40
	s_cselect_b32 s9, s39, s1
	s_cselect_b32 s8, s38, s0
	v_add_u32_e32 v146, s45, v168
	s_cselect_b32 s3, s41, s43
	s_cselect_b32 s2, s40, s42
	s_add_i32 s62, 0, 0x14000
	ds_read_b128 v[128:131], v146
	ds_read_b128 v[132:135], v146 offset:1024
	ds_read_b128 v[158:161], v146 offset:2048
	ds_read_b128 v[162:165], v146 offset:3072
	v_add_u32_e32 v146, s62, v168
	ds_read_b128 v[170:173], v146
	ds_read_b128 v[174:177], v146 offset:1024
	ds_read_b128 v[178:181], v146 offset:2048
	ds_read_b128 v[182:185], v146 offset:3072
	s_add_i32 m0, s50, 0xc000
	ds_read_b128 v[186:189], v169
	ds_read_b128 v[190:193], v169 offset:1024
	ds_read_b128 v[194:197], v169 offset:2048
	ds_read_b128 v[198:201], v169 offset:3072
	ds_read_b128 v[202:205], v169 offset:4096
	ds_read_b128 v[218:221], v169 offset:5120
	ds_read_b128 v[222:225], v169 offset:6144
	ds_read_b128 v[226:229], v169 offset:7168
	global_load_lds_dwordx4 v142, s[4:5]
	s_add_i32 m0, s50, 0xe000
	s_nop 0
	global_load_lds_dwordx4 v144, s[4:5]
	s_cmp_lg_u32 s44, -2
	s_cbranch_scc1 .Lz_skip_1
	v_mov_b64_e32 v[0:1], 0
	v_mov_b64_e32 v[2:3], 0
	v_mov_b64_e32 v[4:5], 0
	v_mov_b64_e32 v[6:7], 0
	v_mov_b64_e32 v[16:17], 0
	v_mov_b64_e32 v[18:19], 0
	v_mov_b64_e32 v[20:21], 0
	v_mov_b64_e32 v[22:23], 0
	v_mov_b64_e32 v[32:33], 0
	v_mov_b64_e32 v[34:35], 0
	v_mov_b64_e32 v[36:37], 0
	v_mov_b64_e32 v[38:39], 0
	v_mov_b64_e32 v[48:49], 0
	v_mov_b64_e32 v[50:51], 0
	v_mov_b64_e32 v[52:53], 0
	v_mov_b64_e32 v[54:55], 0
	v_mov_b64_e32 v[8:9], 0
	v_mov_b64_e32 v[10:11], 0
	v_mov_b64_e32 v[12:13], 0
	v_mov_b64_e32 v[14:15], 0
	v_mov_b64_e32 v[24:25], 0
	v_mov_b64_e32 v[26:27], 0
	v_mov_b64_e32 v[28:29], 0
	v_mov_b64_e32 v[30:31], 0
	v_mov_b64_e32 v[40:41], 0
	v_mov_b64_e32 v[42:43], 0
	v_mov_b64_e32 v[44:45], 0
	v_mov_b64_e32 v[46:47], 0
	v_mov_b64_e32 v[56:57], 0
	v_mov_b64_e32 v[58:59], 0
	v_mov_b64_e32 v[60:61], 0
	v_mov_b64_e32 v[62:63], 0
	v_mov_b64_e32 v[64:65], 0
	v_mov_b64_e32 v[66:67], 0
	v_mov_b64_e32 v[68:69], 0
	v_mov_b64_e32 v[70:71], 0
	v_mov_b64_e32 v[80:81], 0
	v_mov_b64_e32 v[82:83], 0
	v_mov_b64_e32 v[84:85], 0
	v_mov_b64_e32 v[86:87], 0
	v_mov_b64_e32 v[96:97], 0
	v_mov_b64_e32 v[98:99], 0
	v_mov_b64_e32 v[100:101], 0
	v_mov_b64_e32 v[102:103], 0
	v_mov_b64_e32 v[112:113], 0
	v_mov_b64_e32 v[114:115], 0
	v_mov_b64_e32 v[116:117], 0
	v_mov_b64_e32 v[118:119], 0
	v_mov_b64_e32 v[72:73], 0
	v_mov_b64_e32 v[74:75], 0
	v_mov_b64_e32 v[76:77], 0
	v_mov_b64_e32 v[78:79], 0
	v_mov_b64_e32 v[88:89], 0
	v_mov_b64_e32 v[90:91], 0
	v_mov_b64_e32 v[92:93], 0
	v_mov_b64_e32 v[94:95], 0
	v_mov_b64_e32 v[104:105], 0
	v_mov_b64_e32 v[106:107], 0
	v_mov_b64_e32 v[108:109], 0
	v_mov_b64_e32 v[110:111], 0
	v_mov_b64_e32 v[120:121], 0
	v_mov_b64_e32 v[122:123], 0
	v_mov_b64_e32 v[124:125], 0
	v_mov_b64_e32 v[126:127], 0
.Lz_skip_1:
	s_waitcnt vmcnt(8)
	s_waitcnt lgkmcnt(0)
	s_barrier
	s_waitcnt lgkmcnt(0)
	v_mfma_f32_16x16x32_bf16 v[124:127], v[128:131], v[186:189], v[124:127]
	v_mfma_f32_16x16x32_bf16 v[120:123], v[158:161], v[186:189], v[120:123]
	v_mfma_f32_16x16x32_bf16 v[108:111], v[128:131], v[194:197], v[108:111]
	v_mfma_f32_16x16x32_bf16 v[104:107], v[158:161], v[194:197], v[104:107]
	v_mfma_f32_16x16x32_bf16 v[92:95], v[128:131], v[202:205], v[92:95]
	v_mfma_f32_16x16x32_bf16 v[88:91], v[158:161], v[202:205], v[88:91]
	v_mfma_f32_16x16x32_bf16 v[76:79], v[128:131], v[222:225], v[76:79]
	v_mfma_f32_16x16x32_bf16 v[72:75], v[158:161], v[222:225], v[72:75]
	v_mfma_f32_16x16x32_bf16 v[124:127], v[132:135], v[190:193], v[124:127]
	v_mfma_f32_16x16x32_bf16 v[120:123], v[162:165], v[190:193], v[120:123]
	v_mfma_f32_16x16x32_bf16 v[108:111], v[132:135], v[198:201], v[108:111]
	v_mfma_f32_16x16x32_bf16 v[104:107], v[162:165], v[198:201], v[104:107]
	v_mfma_f32_16x16x32_bf16 v[92:95], v[132:135], v[218:221], v[92:95]
	v_mfma_f32_16x16x32_bf16 v[88:91], v[162:165], v[218:221], v[88:91]
	v_mfma_f32_16x16x32_bf16 v[76:79], v[132:135], v[226:229], v[76:79]
	v_mfma_f32_16x16x32_bf16 v[72:75], v[162:165], v[226:229], v[72:75]
	v_mfma_f32_16x16x32_bf16 v[116:119], v[170:173], v[186:189], v[116:119]
	v_mfma_f32_16x16x32_bf16 v[112:115], v[178:181], v[186:189], v[112:115]
	v_mfma_f32_16x16x32_bf16 v[100:103], v[170:173], v[194:197], v[100:103]
	v_mfma_f32_16x16x32_bf16 v[96:99], v[178:181], v[194:197], v[96:99]
	v_mfma_f32_16x16x32_bf16 v[84:87], v[170:173], v[202:205], v[84:87]
	v_mfma_f32_16x16x32_bf16 v[80:83], v[178:181], v[202:205], v[80:83]
	v_mfma_f32_16x16x32_bf16 v[68:71], v[170:173], v[222:225], v[68:71]
	v_mfma_f32_16x16x32_bf16 v[64:67], v[178:181], v[222:225], v[64:67]
	v_mfma_f32_16x16x32_bf16 v[116:119], v[174:177], v[190:193], v[116:119]
	v_mfma_f32_16x16x32_bf16 v[112:115], v[182:185], v[190:193], v[112:115]
	v_mfma_f32_16x16x32_bf16 v[100:103], v[174:177], v[198:201], v[100:103]
	v_mfma_f32_16x16x32_bf16 v[96:99], v[182:185], v[198:201], v[96:99]
	v_mfma_f32_16x16x32_bf16 v[84:87], v[174:177], v[218:221], v[84:87]
	v_mfma_f32_16x16x32_bf16 v[80:83], v[182:185], v[218:221], v[80:83]
	v_mfma_f32_16x16x32_bf16 v[68:71], v[174:177], v[226:229], v[68:71]
	v_mfma_f32_16x16x32_bf16 v[64:67], v[182:185], v[226:229], v[64:67]
	s_barrier
	s_add_i32 s4, s45, s49
	v_lshl_add_u64 v[146:147], s[2:3], 0, v[148:149]
	s_mov_b32 m0, s4
	ds_read_b128 v[186:189], v169 offset:16384
	ds_read_b128 v[190:193], v169 offset:17408
	ds_read_b128 v[194:197], v169 offset:18432
	ds_read_b128 v[198:201], v169 offset:19456
	ds_read_b128 v[202:205], v169 offset:20480
	ds_read_b128 v[218:221], v169 offset:21504
	ds_read_b128 v[222:225], v169 offset:22528
	ds_read_b128 v[226:229], v169 offset:23552
	global_load_lds_dwordx4 v[146:147], off
	s_add_i32 m0, s4, 0x2000
	s_add_u32 s4, s2, 0xb0000
	v_lshl_add_u64 v[154:155], s[2:3], 0, v[136:137]
	s_addc_u32 s5, s3, 0
	s_add_i32 s45, s62, s49
	global_load_lds_dwordx4 v[154:155], off
	s_mov_b32 m0, s45
	v_lshl_add_u64 v[166:167], s[8:9], 0, v[138:139]
	global_load_lds_dwordx4 v148, s[4:5]
	s_add_i32 m0, s45, 0x2000
	s_nop 0
	global_load_lds_dwordx4 v136, s[4:5]
	v_lshl_add_u64 v[156:157], s[8:9], 0, v[140:141]
	s_mov_b32 m0, s50
	s_nop 0
	global_load_lds_dwordx4 v[156:157], off
	s_mov_b32 m0, s51
	s_nop 0
	global_load_lds_dwordx4 v[166:167], off
	s_waitcnt vmcnt(8)
	s_waitcnt lgkmcnt(0)
	s_barrier
	s_waitcnt lgkmcnt(0)
	v_mfma_f32_16x16x32_bf16 v[60:63], v[128:131], v[186:189], v[60:63]
	v_mfma_f32_16x16x32_bf16 v[56:59], v[158:161], v[186:189], v[56:59]
	v_mfma_f32_16x16x32_bf16 v[44:47], v[128:131], v[194:197], v[44:47]
	v_mfma_f32_16x16x32_bf16 v[40:43], v[158:161], v[194:197], v[40:43]
	v_mfma_f32_16x16x32_bf16 v[28:31], v[128:131], v[202:205], v[28:31]
	v_mfma_f32_16x16x32_bf16 v[24:27], v[158:161], v[202:205], v[24:27]
	v_mfma_f32_16x16x32_bf16 v[12:15], v[128:131], v[222:225], v[12:15]
	v_mfma_f32_16x16x32_bf16 v[8:11], v[158:161], v[222:225], v[8:11]
	v_mfma_f32_16x16x32_bf16 v[60:63], v[132:135], v[190:193], v[60:63]
	v_mfma_f32_16x16x32_bf16 v[56:59], v[162:165], v[190:193], v[56:59]
	v_mfma_f32_16x16x32_bf16 v[44:47], v[132:135], v[198:201], v[44:47]
	v_mfma_f32_16x16x32_bf16 v[40:43], v[162:165], v[198:201], v[40:43]
	v_mfma_f32_16x16x32_bf16 v[28:31], v[132:135], v[218:221], v[28:31]
	v_mfma_f32_16x16x32_bf16 v[24:27], v[162:165], v[218:221], v[24:27]
	v_mfma_f32_16x16x32_bf16 v[12:15], v[132:135], v[226:229], v[12:15]
	v_mfma_f32_16x16x32_bf16 v[8:11], v[162:165], v[226:229], v[8:11]
	v_mfma_f32_16x16x32_bf16 v[52:55], v[170:173], v[186:189], v[52:55]
	v_mfma_f32_16x16x32_bf16 v[48:51], v[178:181], v[186:189], v[48:51]
	v_mfma_f32_16x16x32_bf16 v[36:39], v[170:173], v[194:197], v[36:39]
	v_mfma_f32_16x16x32_bf16 v[32:35], v[178:181], v[194:197], v[32:35]
	v_mfma_f32_16x16x32_bf16 v[20:23], v[170:173], v[202:205], v[20:23]
	v_mfma_f32_16x16x32_bf16 v[16:19], v[178:181], v[202:205], v[16:19]
	v_mfma_f32_16x16x32_bf16 v[4:7], v[170:173], v[222:225], v[4:7]
	v_mfma_f32_16x16x32_bf16 v[0:3], v[178:181], v[222:225], v[0:3]
	v_mfma_f32_16x16x32_bf16 v[52:55], v[174:177], v[190:193], v[52:55]
	v_mfma_f32_16x16x32_bf16 v[48:51], v[182:185], v[190:193], v[48:51]
	v_mfma_f32_16x16x32_bf16 v[36:39], v[174:177], v[198:201], v[36:39]
	v_mfma_f32_16x16x32_bf16 v[32:35], v[182:185], v[198:201], v[32:35]
	v_mfma_f32_16x16x32_bf16 v[20:23], v[174:177], v[218:221], v[20:23]
	v_mfma_f32_16x16x32_bf16 v[16:19], v[182:185], v[218:221], v[16:19]
	v_mfma_f32_16x16x32_bf16 v[4:7], v[174:177], v[226:229], v[4:7]
	v_mfma_f32_16x16x32_bf16 v[0:3], v[182:185], v[226:229], v[0:3]
	s_barrier
	s_add_i32 s45, 0, 0x18000
	v_add_u32_e32 v150, s45, v168
	s_add_i32 s62, 0, 0x1c000
	ds_read_b128 v[128:131], v150
	ds_read_b128 v[132:135], v150 offset:1024
	ds_read_b128 v[158:161], v150 offset:2048
	ds_read_b128 v[162:165], v150 offset:3072
	v_add_u32_e32 v150, s62, v168
	ds_read_b128 v[170:173], v150
	ds_read_b128 v[174:177], v150 offset:1024
	ds_read_b128 v[178:181], v150 offset:2048
	ds_read_b128 v[182:185], v150 offset:3072
	s_add_u32 s4, s8, 0xb0000
	s_addc_u32 s5, s9, 0
	s_mov_b32 m0, s52
	ds_read_b128 v[186:189], v169 offset:32768
	ds_read_b128 v[190:193], v169 offset:33792
	ds_read_b128 v[194:197], v169 offset:34816
	ds_read_b128 v[198:201], v169 offset:35840
	ds_read_b128 v[202:205], v169 offset:36864
	ds_read_b128 v[218:221], v169 offset:37888
	ds_read_b128 v[222:225], v169 offset:38912
	ds_read_b128 v[226:229], v169 offset:39936
	global_load_lds_dwordx4 v140, s[4:5]
	s_mov_b32 m0, s53
	s_nop 0
	global_load_lds_dwordx4 v138, s[4:5]
	s_waitcnt vmcnt(8)
	s_waitcnt lgkmcnt(0)
	s_barrier
	s_waitcnt lgkmcnt(0)
	v_mfma_f32_16x16x32_bf16 v[124:127], v[128:131], v[186:189], v[124:127]
	v_mfma_f32_16x16x32_bf16 v[120:123], v[158:161], v[186:189], v[120:123]
	v_mfma_f32_16x16x32_bf16 v[108:111], v[128:131], v[194:197], v[108:111]
	v_mfma_f32_16x16x32_bf16 v[104:107], v[158:161], v[194:197], v[104:107]
	v_mfma_f32_16x16x32_bf16 v[92:95], v[128:131], v[202:205], v[92:95]
	v_mfma_f32_16x16x32_bf16 v[88:91], v[158:161], v[202:205], v[88:91]
	v_mfma_f32_16x16x32_bf16 v[76:79], v[128:131], v[222:225], v[76:79]
	v_mfma_f32_16x16x32_bf16 v[72:75], v[158:161], v[222:225], v[72:75]
	v_mfma_f32_16x16x32_bf16 v[124:127], v[132:135], v[190:193], v[124:127]
	v_mfma_f32_16x16x32_bf16 v[120:123], v[162:165], v[190:193], v[120:123]
	v_mfma_f32_16x16x32_bf16 v[108:111], v[132:135], v[198:201], v[108:111]
	v_mfma_f32_16x16x32_bf16 v[104:107], v[162:165], v[198:201], v[104:107]
	v_mfma_f32_16x16x32_bf16 v[92:95], v[132:135], v[218:221], v[92:95]
	v_mfma_f32_16x16x32_bf16 v[88:91], v[162:165], v[218:221], v[88:91]
	v_mfma_f32_16x16x32_bf16 v[76:79], v[132:135], v[226:229], v[76:79]
	v_mfma_f32_16x16x32_bf16 v[72:75], v[162:165], v[226:229], v[72:75]
	v_mfma_f32_16x16x32_bf16 v[116:119], v[170:173], v[186:189], v[116:119]
	v_mfma_f32_16x16x32_bf16 v[112:115], v[178:181], v[186:189], v[112:115]
	v_mfma_f32_16x16x32_bf16 v[100:103], v[170:173], v[194:197], v[100:103]
	v_mfma_f32_16x16x32_bf16 v[96:99], v[178:181], v[194:197], v[96:99]
	v_mfma_f32_16x16x32_bf16 v[84:87], v[170:173], v[202:205], v[84:87]
	v_mfma_f32_16x16x32_bf16 v[80:83], v[178:181], v[202:205], v[80:83]
	v_mfma_f32_16x16x32_bf16 v[68:71], v[170:173], v[222:225], v[68:71]
	v_mfma_f32_16x16x32_bf16 v[64:67], v[178:181], v[222:225], v[64:67]
	v_mfma_f32_16x16x32_bf16 v[116:119], v[174:177], v[190:193], v[116:119]
	v_mfma_f32_16x16x32_bf16 v[112:115], v[182:185], v[190:193], v[112:115]
	v_mfma_f32_16x16x32_bf16 v[100:103], v[174:177], v[198:201], v[100:103]
	v_mfma_f32_16x16x32_bf16 v[96:99], v[182:185], v[198:201], v[96:99]
	v_mfma_f32_16x16x32_bf16 v[84:87], v[174:177], v[218:221], v[84:87]
	v_mfma_f32_16x16x32_bf16 v[80:83], v[182:185], v[218:221], v[80:83]
	v_mfma_f32_16x16x32_bf16 v[68:71], v[174:177], v[226:229], v[68:71]
	v_mfma_f32_16x16x32_bf16 v[64:67], v[182:185], v[226:229], v[64:67]
	s_barrier
	s_add_i32 s4, s45, s49
	v_lshl_add_u64 v[146:147], v[146:147], 0, s[28:29]
	s_mov_b32 m0, s4
	ds_read_b128 v[186:189], v169 offset:49152
	ds_read_b128 v[190:193], v169 offset:50176
	ds_read_b128 v[194:197], v169 offset:51200
	ds_read_b128 v[198:201], v169 offset:52224
	ds_read_b128 v[202:205], v169 offset:53248
	ds_read_b128 v[218:221], v169 offset:54272
	ds_read_b128 v[222:225], v169 offset:55296
	ds_read_b128 v[226:229], v169 offset:56320
	global_load_lds_dwordx4 v[146:147], off
	s_add_i32 m0, s4, 0x2000
	s_add_u32 s2, s2, 0xb0080
	v_lshl_add_u64 v[146:147], v[154:155], 0, s[28:29]
	s_addc_u32 s3, s3, 0
	s_add_i32 s4, s62, s49
	global_load_lds_dwordx4 v[146:147], off
	s_mov_b32 m0, s4
	s_nop 0
	global_load_lds_dwordx4 v148, s[2:3]
	s_add_i32 m0, s4, 0x2000
	s_nop 0
	global_load_lds_dwordx4 v136, s[2:3]
	v_lshl_add_u64 v[146:147], v[156:157], 0, s[28:29]
	s_mov_b32 m0, s57
	s_nop 0
	global_load_lds_dwordx4 v[146:147], off
	v_lshl_add_u64 v[146:147], v[166:167], 0, s[28:29]
	s_mov_b32 m0, s58
	s_nop 0
	global_load_lds_dwordx4 v[146:147], off
	s_waitcnt vmcnt(8)
	s_waitcnt lgkmcnt(0)
	s_barrier
	s_waitcnt lgkmcnt(0)
	v_mfma_f32_16x16x32_bf16 v[60:63], v[128:131], v[186:189], v[60:63]
	v_mfma_f32_16x16x32_bf16 v[56:59], v[158:161], v[186:189], v[56:59]
	v_mfma_f32_16x16x32_bf16 v[44:47], v[128:131], v[194:197], v[44:47]
	v_mfma_f32_16x16x32_bf16 v[40:43], v[158:161], v[194:197], v[40:43]
	v_mfma_f32_16x16x32_bf16 v[28:31], v[128:131], v[202:205], v[28:31]
	v_mfma_f32_16x16x32_bf16 v[24:27], v[158:161], v[202:205], v[24:27]
	v_mfma_f32_16x16x32_bf16 v[12:15], v[128:131], v[222:225], v[12:15]
	v_mfma_f32_16x16x32_bf16 v[8:11], v[158:161], v[222:225], v[8:11]
	v_mfma_f32_16x16x32_bf16 v[60:63], v[132:135], v[190:193], v[60:63]
	v_mfma_f32_16x16x32_bf16 v[56:59], v[162:165], v[190:193], v[56:59]
	v_mfma_f32_16x16x32_bf16 v[44:47], v[132:135], v[198:201], v[44:47]
	v_mfma_f32_16x16x32_bf16 v[40:43], v[162:165], v[198:201], v[40:43]
	v_mfma_f32_16x16x32_bf16 v[28:31], v[132:135], v[218:221], v[28:31]
	v_mfma_f32_16x16x32_bf16 v[24:27], v[162:165], v[218:221], v[24:27]
	v_mfma_f32_16x16x32_bf16 v[12:15], v[132:135], v[226:229], v[12:15]
	v_mfma_f32_16x16x32_bf16 v[8:11], v[162:165], v[226:229], v[8:11]
	v_mfma_f32_16x16x32_bf16 v[52:55], v[170:173], v[186:189], v[52:55]
	v_mfma_f32_16x16x32_bf16 v[48:51], v[178:181], v[186:189], v[48:51]
	v_mfma_f32_16x16x32_bf16 v[36:39], v[170:173], v[194:197], v[36:39]
	v_mfma_f32_16x16x32_bf16 v[32:35], v[178:181], v[194:197], v[32:35]
	v_mfma_f32_16x16x32_bf16 v[20:23], v[170:173], v[202:205], v[20:23]
	v_mfma_f32_16x16x32_bf16 v[16:19], v[178:181], v[202:205], v[16:19]
	v_mfma_f32_16x16x32_bf16 v[4:7], v[170:173], v[222:225], v[4:7]
	v_mfma_f32_16x16x32_bf16 v[0:3], v[178:181], v[222:225], v[0:3]
	v_mfma_f32_16x16x32_bf16 v[52:55], v[174:177], v[190:193], v[52:55]
	v_mfma_f32_16x16x32_bf16 v[48:51], v[182:185], v[190:193], v[48:51]
	v_mfma_f32_16x16x32_bf16 v[36:39], v[174:177], v[198:201], v[36:39]
	v_mfma_f32_16x16x32_bf16 v[32:35], v[182:185], v[198:201], v[32:35]
	v_mfma_f32_16x16x32_bf16 v[20:23], v[174:177], v[218:221], v[20:23]
	v_mfma_f32_16x16x32_bf16 v[16:19], v[182:185], v[218:221], v[16:19]
	v_mfma_f32_16x16x32_bf16 v[4:7], v[174:177], v[226:229], v[4:7]
	v_mfma_f32_16x16x32_bf16 v[0:3], v[182:185], v[226:229], v[0:3]
	s_barrier
	s_add_i32 s44, s44, 2
	s_add_u32 s42, s42, 0x100
	s_addc_u32 s43, s43, 0
	s_cmp_gt_u32 s44, 41
	s_mov_b64 s[4:5], s[0:1]
	s_cbranch_scc0 .LBB0_360
	s_and_b64 vcc, exec, s[30:31]
	s_cbranch_vccz .LBB0_363
	s_barrier

.LBB0_588:
	s_add_u32 s12, s10, 0xfffc0080
	s_addc_u32 s13, s11, -1
	s_add_i32 s44, 0, 0x10000
	s_cmp_eq_u32 s43, 12
	s_cselect_b32 s15, s9, s13
	s_cselect_b32 s14, s16, s12
	v_add_u32_e32 v146, s44, v144
	s_cselect_b32 s13, s17, s42
	s_cselect_b32 s12, s35, s37
	s_add_i32 s46, 0, 0x14000
	ds_read_b128 v[140:143], v146
	ds_read_b128 v[158:161], v146 offset:1024
	ds_read_b128 v[162:165], v146 offset:2048
	ds_read_b128 v[166:169], v146 offset:3072
	v_add_u32_e32 v146, s46, v144
	ds_read_b128 v[174:177], v146
	ds_read_b128 v[178:181], v146 offset:1024
	ds_read_b128 v[182:185], v146 offset:2048
	ds_read_b128 v[186:189], v146 offset:3072
	s_add_i32 m0, s57, 0xc000
	ds_read_b128 v[190:193], v145
	ds_read_b128 v[194:197], v145 offset:1024
	ds_read_b128 v[198:201], v145 offset:2048
	ds_read_b128 v[202:205], v145 offset:3072
	ds_read_b128 v[218:221], v145 offset:4096
	ds_read_b128 v[222:225], v145 offset:5120
	ds_read_b128 v[226:229], v145 offset:6144
	ds_read_b128 v[230:233], v145 offset:7168
	global_load_lds_dwordx4 v136, s[10:11]
	s_add_i32 m0, s57, 0xe000
	s_nop 0
	global_load_lds_dwordx4 v138, s[10:11]
	s_cmp_lg_u32 s43, -2
	s_cbranch_scc1 .Lz_skip_2
	v_mov_b64_e32 v[0:1], 0
	v_mov_b64_e32 v[2:3], 0
	v_mov_b64_e32 v[4:5], 0
	v_mov_b64_e32 v[6:7], 0
	v_mov_b64_e32 v[16:17], 0
	v_mov_b64_e32 v[18:19], 0
	v_mov_b64_e32 v[20:21], 0
	v_mov_b64_e32 v[22:23], 0
	v_mov_b64_e32 v[32:33], 0
	v_mov_b64_e32 v[34:35], 0
	v_mov_b64_e32 v[36:37], 0
	v_mov_b64_e32 v[38:39], 0
	v_mov_b64_e32 v[48:49], 0
	v_mov_b64_e32 v[50:51], 0
	v_mov_b64_e32 v[52:53], 0
	v_mov_b64_e32 v[54:55], 0
	v_mov_b64_e32 v[8:9], 0
	v_mov_b64_e32 v[10:11], 0
	v_mov_b64_e32 v[12:13], 0
	v_mov_b64_e32 v[14:15], 0
	v_mov_b64_e32 v[24:25], 0
	v_mov_b64_e32 v[26:27], 0
	v_mov_b64_e32 v[28:29], 0
	v_mov_b64_e32 v[30:31], 0
	v_mov_b64_e32 v[40:41], 0
	v_mov_b64_e32 v[42:43], 0
	v_mov_b64_e32 v[44:45], 0
	v_mov_b64_e32 v[46:47], 0
	v_mov_b64_e32 v[56:57], 0
	v_mov_b64_e32 v[58:59], 0
	v_mov_b64_e32 v[60:61], 0
	v_mov_b64_e32 v[62:63], 0
	v_mov_b64_e32 v[64:65], 0
	v_mov_b64_e32 v[66:67], 0
	v_mov_b64_e32 v[68:69], 0
	v_mov_b64_e32 v[70:71], 0
	v_mov_b64_e32 v[80:81], 0
	v_mov_b64_e32 v[82:83], 0
	v_mov_b64_e32 v[84:85], 0
	v_mov_b64_e32 v[86:87], 0
	v_mov_b64_e32 v[96:97], 0
	v_mov_b64_e32 v[98:99], 0
	v_mov_b64_e32 v[100:101], 0
	v_mov_b64_e32 v[102:103], 0
	v_mov_b64_e32 v[112:113], 0
	v_mov_b64_e32 v[114:115], 0
	v_mov_b64_e32 v[116:117], 0
	v_mov_b64_e32 v[118:119], 0
	v_mov_b64_e32 v[72:73], 0
	v_mov_b64_e32 v[74:75], 0
	v_mov_b64_e32 v[76:77], 0
	v_mov_b64_e32 v[78:79], 0
	v_mov_b64_e32 v[88:89], 0
	v_mov_b64_e32 v[90:91], 0
	v_mov_b64_e32 v[92:93], 0
	v_mov_b64_e32 v[94:95], 0
	v_mov_b64_e32 v[104:105], 0
	v_mov_b64_e32 v[106:107], 0
	v_mov_b64_e32 v[108:109], 0
	v_mov_b64_e32 v[110:111], 0
	v_mov_b64_e32 v[120:121], 0
	v_mov_b64_e32 v[122:123], 0
	v_mov_b64_e32 v[124:125], 0
	v_mov_b64_e32 v[126:127], 0
.Lz_skip_2:
	s_waitcnt vmcnt(8)
	s_waitcnt lgkmcnt(0)
	s_barrier
	s_waitcnt lgkmcnt(0)
	v_mfma_f32_16x16x32_bf16 v[124:127], v[140:143], v[190:193], v[124:127]
	v_mfma_f32_16x16x32_bf16 v[120:123], v[162:165], v[190:193], v[120:123]
	v_mfma_f32_16x16x32_bf16 v[108:111], v[140:143], v[198:201], v[108:111]
	v_mfma_f32_16x16x32_bf16 v[104:107], v[162:165], v[198:201], v[104:107]
	v_mfma_f32_16x16x32_bf16 v[92:95], v[140:143], v[218:221], v[92:95]
	v_mfma_f32_16x16x32_bf16 v[88:91], v[162:165], v[218:221], v[88:91]
	v_mfma_f32_16x16x32_bf16 v[76:79], v[140:143], v[226:229], v[76:79]
	v_mfma_f32_16x16x32_bf16 v[72:75], v[162:165], v[226:229], v[72:75]
	v_mfma_f32_16x16x32_bf16 v[124:127], v[158:161], v[194:197], v[124:127]
	v_mfma_f32_16x16x32_bf16 v[120:123], v[166:169], v[194:197], v[120:123]
	v_mfma_f32_16x16x32_bf16 v[108:111], v[158:161], v[202:205], v[108:111]
	v_mfma_f32_16x16x32_bf16 v[104:107], v[166:169], v[202:205], v[104:107]
	v_mfma_f32_16x16x32_bf16 v[92:95], v[158:161], v[222:225], v[92:95]
	v_mfma_f32_16x16x32_bf16 v[88:91], v[166:169], v[222:225], v[88:91]
	v_mfma_f32_16x16x32_bf16 v[76:79], v[158:161], v[230:233], v[76:79]
	v_mfma_f32_16x16x32_bf16 v[72:75], v[166:169], v[230:233], v[72:75]
	v_mfma_f32_16x16x32_bf16 v[116:119], v[174:177], v[190:193], v[116:119]
	v_mfma_f32_16x16x32_bf16 v[112:115], v[182:185], v[190:193], v[112:115]
	v_mfma_f32_16x16x32_bf16 v[100:103], v[174:177], v[198:201], v[100:103]
	v_mfma_f32_16x16x32_bf16 v[96:99], v[182:185], v[198:201], v[96:99]
	v_mfma_f32_16x16x32_bf16 v[84:87], v[174:177], v[218:221], v[84:87]
	v_mfma_f32_16x16x32_bf16 v[80:83], v[182:185], v[218:221], v[80:83]
	v_mfma_f32_16x16x32_bf16 v[68:71], v[174:177], v[226:229], v[68:71]
	v_mfma_f32_16x16x32_bf16 v[64:67], v[182:185], v[226:229], v[64:67]
	v_mfma_f32_16x16x32_bf16 v[116:119], v[178:181], v[194:197], v[116:119]
	v_mfma_f32_16x16x32_bf16 v[112:115], v[186:189], v[194:197], v[112:115]
	v_mfma_f32_16x16x32_bf16 v[100:103], v[178:181], v[202:205], v[100:103]
	v_mfma_f32_16x16x32_bf16 v[96:99], v[186:189], v[202:205], v[96:99]
	v_mfma_f32_16x16x32_bf16 v[84:87], v[178:181], v[222:225], v[84:87]
	v_mfma_f32_16x16x32_bf16 v[80:83], v[186:189], v[222:225], v[80:83]
	v_mfma_f32_16x16x32_bf16 v[68:71], v[178:181], v[230:233], v[68:71]
	v_mfma_f32_16x16x32_bf16 v[64:67], v[186:189], v[230:233], v[64:67]
	s_barrier
	s_add_i32 s44, s44, s56
	v_lshl_add_u64 v[146:147], s[12:13], 0, v[132:133]
	s_mov_b32 m0, s44
	ds_read_b128 v[190:193], v145 offset:16384
	ds_read_b128 v[194:197], v145 offset:17408
	ds_read_b128 v[198:201], v145 offset:18432
	ds_read_b128 v[202:205], v145 offset:19456
	ds_read_b128 v[218:221], v145 offset:20480
	ds_read_b128 v[222:225], v145 offset:21504
	ds_read_b128 v[226:229], v145 offset:22528
	ds_read_b128 v[230:233], v145 offset:23552
	global_load_lds_dwordx4 v[146:147], off
	s_add_i32 m0, s44, 0x2000
	s_add_u32 s44, s12, 0x40000
	v_lshl_add_u64 v[154:155], s[12:13], 0, v[128:129]
	s_addc_u32 s45, s13, 0
	s_add_i32 s46, s46, s56
	global_load_lds_dwordx4 v[154:155], off
	s_mov_b32 m0, s46
	v_lshl_add_u64 v[170:171], s[14:15], 0, v[130:131]
	global_load_lds_dwordx4 v132, s[44:45]
	s_add_i32 m0, s46, 0x2000
	s_nop 0
	global_load_lds_dwordx4 v128, s[44:45]
	v_lshl_add_u64 v[156:157], s[14:15], 0, v[134:135]
	s_mov_b32 m0, s57
	s_nop 0
	global_load_lds_dwordx4 v[156:157], off
	s_mov_b32 m0, s58
	s_nop 0
	global_load_lds_dwordx4 v[170:171], off
	s_waitcnt vmcnt(8)
	s_waitcnt lgkmcnt(0)
	s_barrier
	s_waitcnt lgkmcnt(0)
	v_mfma_f32_16x16x32_bf16 v[60:63], v[140:143], v[190:193], v[60:63]
	v_mfma_f32_16x16x32_bf16 v[56:59], v[162:165], v[190:193], v[56:59]
	v_mfma_f32_16x16x32_bf16 v[44:47], v[140:143], v[198:201], v[44:47]
	v_mfma_f32_16x16x32_bf16 v[40:43], v[162:165], v[198:201], v[40:43]
	v_mfma_f32_16x16x32_bf16 v[28:31], v[140:143], v[218:221], v[28:31]
	v_mfma_f32_16x16x32_bf16 v[24:27], v[162:165], v[218:221], v[24:27]
	v_mfma_f32_16x16x32_bf16 v[12:15], v[140:143], v[226:229], v[12:15]
	v_mfma_f32_16x16x32_bf16 v[8:11], v[162:165], v[226:229], v[8:11]
	v_mfma_f32_16x16x32_bf16 v[60:63], v[158:161], v[194:197], v[60:63]
	v_mfma_f32_16x16x32_bf16 v[56:59], v[166:169], v[194:197], v[56:59]
	v_mfma_f32_16x16x32_bf16 v[44:47], v[158:161], v[202:205], v[44:47]
	v_mfma_f32_16x16x32_bf16 v[40:43], v[166:169], v[202:205], v[40:43]
	v_mfma_f32_16x16x32_bf16 v[28:31], v[158:161], v[222:225], v[28:31]
	v_mfma_f32_16x16x32_bf16 v[24:27], v[166:169], v[222:225], v[24:27]
	v_mfma_f32_16x16x32_bf16 v[12:15], v[158:161], v[230:233], v[12:15]
	v_mfma_f32_16x16x32_bf16 v[8:11], v[166:169], v[230:233], v[8:11]
	v_mfma_f32_16x16x32_bf16 v[52:55], v[174:177], v[190:193], v[52:55]
	v_mfma_f32_16x16x32_bf16 v[48:51], v[182:185], v[190:193], v[48:51]
	v_mfma_f32_16x16x32_bf16 v[36:39], v[174:177], v[198:201], v[36:39]
	v_mfma_f32_16x16x32_bf16 v[32:35], v[182:185], v[198:201], v[32:35]
	v_mfma_f32_16x16x32_bf16 v[20:23], v[174:177], v[218:221], v[20:23]
	v_mfma_f32_16x16x32_bf16 v[16:19], v[182:185], v[218:221], v[16:19]
	v_mfma_f32_16x16x32_bf16 v[4:7], v[174:177], v[226:229], v[4:7]
	v_mfma_f32_16x16x32_bf16 v[0:3], v[182:185], v[226:229], v[0:3]
	v_mfma_f32_16x16x32_bf16 v[52:55], v[178:181], v[194:197], v[52:55]
	v_mfma_f32_16x16x32_bf16 v[48:51], v[186:189], v[194:197], v[48:51]
	v_mfma_f32_16x16x32_bf16 v[36:39], v[178:181], v[202:205], v[36:39]
	v_mfma_f32_16x16x32_bf16 v[32:35], v[186:189], v[202:205], v[32:35]
	v_mfma_f32_16x16x32_bf16 v[20:23], v[178:181], v[222:225], v[20:23]
	v_mfma_f32_16x16x32_bf16 v[16:19], v[186:189], v[222:225], v[16:19]
	v_mfma_f32_16x16x32_bf16 v[4:7], v[178:181], v[230:233], v[4:7]
	v_mfma_f32_16x16x32_bf16 v[0:3], v[186:189], v[230:233], v[0:3]
	s_barrier
	s_add_i32 s44, 0, 0x18000
	v_add_u32_e32 v148, s44, v144
	s_add_i32 s45, 0, 0x1c000
	ds_read_b128 v[140:143], v148
	ds_read_b128 v[158:161], v148 offset:1024
	ds_read_b128 v[162:165], v148 offset:2048
	ds_read_b128 v[166:169], v148 offset:3072
	v_add_u32_e32 v148, s45, v144
	ds_read_b128 v[174:177], v148
	ds_read_b128 v[178:181], v148 offset:1024
	ds_read_b128 v[182:185], v148 offset:2048
	ds_read_b128 v[186:189], v148 offset:3072
	s_add_u32 s14, s14, 0x40000
	s_addc_u32 s15, s15, 0
	s_mov_b32 m0, s59
	ds_read_b128 v[190:193], v145 offset:32768
	ds_read_b128 v[194:197], v145 offset:33792
	ds_read_b128 v[198:201], v145 offset:34816
	ds_read_b128 v[202:205], v145 offset:35840
	ds_read_b128 v[218:221], v145 offset:36864
	ds_read_b128 v[222:225], v145 offset:37888
	ds_read_b128 v[226:229], v145 offset:38912
	ds_read_b128 v[230:233], v145 offset:39936
	global_load_lds_dwordx4 v134, s[14:15]
	s_mov_b32 m0, s60
	s_nop 0
	global_load_lds_dwordx4 v130, s[14:15]
	s_waitcnt vmcnt(8)
	s_waitcnt lgkmcnt(0)
	s_barrier
	s_waitcnt lgkmcnt(0)
	v_mfma_f32_16x16x32_bf16 v[124:127], v[140:143], v[190:193], v[124:127]
	v_mfma_f32_16x16x32_bf16 v[120:123], v[162:165], v[190:193], v[120:123]
	v_mfma_f32_16x16x32_bf16 v[108:111], v[140:143], v[198:201], v[108:111]
	v_mfma_f32_16x16x32_bf16 v[104:107], v[162:165], v[198:201], v[104:107]
	v_mfma_f32_16x16x32_bf16 v[92:95], v[140:143], v[218:221], v[92:95]
	v_mfma_f32_16x16x32_bf16 v[88:91], v[162:165], v[218:221], v[88:91]
	v_mfma_f32_16x16x32_bf16 v[76:79], v[140:143], v[226:229], v[76:79]
	v_mfma_f32_16x16x32_bf16 v[72:75], v[162:165], v[226:229], v[72:75]
	v_mfma_f32_16x16x32_bf16 v[124:127], v[158:161], v[194:197], v[124:127]
	v_mfma_f32_16x16x32_bf16 v[120:123], v[166:169], v[194:197], v[120:123]
	v_mfma_f32_16x16x32_bf16 v[108:111], v[158:161], v[202:205], v[108:111]
	v_mfma_f32_16x16x32_bf16 v[104:107], v[166:169], v[202:205], v[104:107]
	v_mfma_f32_16x16x32_bf16 v[92:95], v[158:161], v[222:225], v[92:95]
	v_mfma_f32_16x16x32_bf16 v[88:91], v[166:169], v[222:225], v[88:91]
	v_mfma_f32_16x16x32_bf16 v[76:79], v[158:161], v[230:233], v[76:79]
	v_mfma_f32_16x16x32_bf16 v[72:75], v[166:169], v[230:233], v[72:75]
	v_mfma_f32_16x16x32_bf16 v[116:119], v[174:177], v[190:193], v[116:119]
	v_mfma_f32_16x16x32_bf16 v[112:115], v[182:185], v[190:193], v[112:115]
	v_mfma_f32_16x16x32_bf16 v[100:103], v[174:177], v[198:201], v[100:103]
	v_mfma_f32_16x16x32_bf16 v[96:99], v[182:185], v[198:201], v[96:99]
	v_mfma_f32_16x16x32_bf16 v[84:87], v[174:177], v[218:221], v[84:87]
	v_mfma_f32_16x16x32_bf16 v[80:83], v[182:185], v[218:221], v[80:83]
	v_mfma_f32_16x16x32_bf16 v[68:71], v[174:177], v[226:229], v[68:71]
	v_mfma_f32_16x16x32_bf16 v[64:67], v[182:185], v[226:229], v[64:67]
	v_mfma_f32_16x16x32_bf16 v[116:119], v[178:181], v[194:197], v[116:119]
	v_mfma_f32_16x16x32_bf16 v[112:115], v[186:189], v[194:197], v[112:115]
	v_mfma_f32_16x16x32_bf16 v[100:103], v[178:181], v[202:205], v[100:103]
	v_mfma_f32_16x16x32_bf16 v[96:99], v[186:189], v[202:205], v[96:99]
	v_mfma_f32_16x16x32_bf16 v[84:87], v[178:181], v[222:225], v[84:87]
	v_mfma_f32_16x16x32_bf16 v[80:83], v[186:189], v[222:225], v[80:83]
	v_mfma_f32_16x16x32_bf16 v[68:71], v[178:181], v[230:233], v[68:71]
	v_mfma_f32_16x16x32_bf16 v[64:67], v[186:189], v[230:233], v[64:67]
	s_barrier
	s_add_i32 s14, s44, s56
	v_lshl_add_u64 v[146:147], v[146:147], 0, s[28:29]
	s_mov_b32 m0, s14
	ds_read_b128 v[190:193], v145 offset:49152
	ds_read_b128 v[194:197], v145 offset:50176
	ds_read_b128 v[198:201], v145 offset:51200
	ds_read_b128 v[202:205], v145 offset:52224
	ds_read_b128 v[218:221], v145 offset:53248
	ds_read_b128 v[222:225], v145 offset:54272
	ds_read_b128 v[226:229], v145 offset:55296
	ds_read_b128 v[230:233], v145 offset:56320
	global_load_lds_dwordx4 v[146:147], off
	s_add_i32 m0, s14, 0x2000
	s_add_u32 s12, s12, 0x40080
	v_lshl_add_u64 v[146:147], v[154:155], 0, s[28:29]
	s_addc_u32 s13, s13, 0
	s_add_i32 s14, s45, s56
	global_load_lds_dwordx4 v[146:147], off
	s_mov_b32 m0, s14
	s_nop 0
	global_load_lds_dwordx4 v132, s[12:13]
	s_add_i32 m0, s14, 0x2000
	s_nop 0
	global_load_lds_dwordx4 v128, s[12:13]
	v_lshl_add_u64 v[146:147], v[156:157], 0, s[28:29]
	s_mov_b32 m0, s72
	s_nop 0
	global_load_lds_dwordx4 v[146:147], off
	v_lshl_add_u64 v[146:147], v[170:171], 0, s[28:29]
	s_mov_b32 m0, s73
	s_nop 0
	global_load_lds_dwordx4 v[146:147], off
	s_waitcnt vmcnt(8)
	s_waitcnt lgkmcnt(0)
	s_barrier
	s_waitcnt lgkmcnt(0)
	v_mfma_f32_16x16x32_bf16 v[60:63], v[140:143], v[190:193], v[60:63]
	v_mfma_f32_16x16x32_bf16 v[56:59], v[162:165], v[190:193], v[56:59]
	v_mfma_f32_16x16x32_bf16 v[44:47], v[140:143], v[198:201], v[44:47]
	v_mfma_f32_16x16x32_bf16 v[40:43], v[162:165], v[198:201], v[40:43]
	v_mfma_f32_16x16x32_bf16 v[28:31], v[140:143], v[218:221], v[28:31]
	v_mfma_f32_16x16x32_bf16 v[24:27], v[162:165], v[218:221], v[24:27]
	v_mfma_f32_16x16x32_bf16 v[12:15], v[140:143], v[226:229], v[12:15]
	v_mfma_f32_16x16x32_bf16 v[8:11], v[162:165], v[226:229], v[8:11]
	v_mfma_f32_16x16x32_bf16 v[60:63], v[158:161], v[194:197], v[60:63]
	v_mfma_f32_16x16x32_bf16 v[56:59], v[166:169], v[194:197], v[56:59]
	v_mfma_f32_16x16x32_bf16 v[44:47], v[158:161], v[202:205], v[44:47]
	v_mfma_f32_16x16x32_bf16 v[40:43], v[166:169], v[202:205], v[40:43]
	v_mfma_f32_16x16x32_bf16 v[28:31], v[158:161], v[222:225], v[28:31]
	v_mfma_f32_16x16x32_bf16 v[24:27], v[166:169], v[222:225], v[24:27]
	v_mfma_f32_16x16x32_bf16 v[12:15], v[158:161], v[230:233], v[12:15]
	v_mfma_f32_16x16x32_bf16 v[8:11], v[166:169], v[230:233], v[8:11]
	v_mfma_f32_16x16x32_bf16 v[52:55], v[174:177], v[190:193], v[52:55]
	v_mfma_f32_16x16x32_bf16 v[48:51], v[182:185], v[190:193], v[48:51]
	v_mfma_f32_16x16x32_bf16 v[36:39], v[174:177], v[198:201], v[36:39]
	v_mfma_f32_16x16x32_bf16 v[32:35], v[182:185], v[198:201], v[32:35]
	v_mfma_f32_16x16x32_bf16 v[20:23], v[174:177], v[218:221], v[20:23]
	v_mfma_f32_16x16x32_bf16 v[16:19], v[182:185], v[218:221], v[16:19]
	v_mfma_f32_16x16x32_bf16 v[4:7], v[174:177], v[226:229], v[4:7]
	v_mfma_f32_16x16x32_bf16 v[0:3], v[182:185], v[226:229], v[0:3]
	v_mfma_f32_16x16x32_bf16 v[52:55], v[178:181], v[194:197], v[52:55]
	v_mfma_f32_16x16x32_bf16 v[48:51], v[186:189], v[194:197], v[48:51]
	v_mfma_f32_16x16x32_bf16 v[36:39], v[178:181], v[202:205], v[36:39]
	v_mfma_f32_16x16x32_bf16 v[32:35], v[186:189], v[202:205], v[32:35]
	v_mfma_f32_16x16x32_bf16 v[20:23], v[178:181], v[222:225], v[20:23]
	v_mfma_f32_16x16x32_bf16 v[16:19], v[186:189], v[222:225], v[16:19]
	v_mfma_f32_16x16x32_bf16 v[4:7], v[178:181], v[230:233], v[4:7]
	v_mfma_f32_16x16x32_bf16 v[0:3], v[186:189], v[230:233], v[0:3]
	s_barrier
	s_add_i32 s43, s43, 2
	s_add_u32 s10, s10, 0x100
	s_addc_u32 s11, s11, 0
	s_add_u32 s37, s37, 0x100
	s_addc_u32 s42, s42, 0
	s_cmp_gt_u32 s43, 13
	s_cbranch_scc0 .LBB0_588
	s_and_b64 vcc, exec, s[26:27]
	s_cbranch_vccz .LBB0_591
	s_barrier

.LBB0_764:
	s_add_u32 s30, s26, 0xfffc0080
	s_addc_u32 s31, s27, -1
	s_add_i32 s53, 0, 0x10000
	s_cmp_eq_u32 s52, 12
	s_cselect_b32 s35, s21, s31
	s_cselect_b32 s34, s48, s30
	s_cselect_b32 s31, s19, s51
	s_cselect_b32 s30, s49, s50
	s_add_i32 s56, 0, 0x14000
	v_add_u32_e32 v140, s53, v173
	v_add_u32_e32 v150, s56, v173
	ds_read_b128 v[128:131], v140
	ds_read_b128 v[132:135], v140 offset:1024
	ds_read_b128 v[136:139], v140 offset:2048
	ds_read_b128 v[140:143], v140 offset:3072
	ds_read_b128 v[164:167], v150
	ds_read_b128 v[168:171], v150 offset:1024
	ds_read_b128 v[176:179], v150 offset:2048
	ds_read_b128 v[180:183], v150 offset:3072
	s_add_i32 m0, s37, 0xc000
	ds_read_b128 v[184:187], v174
	ds_read_b128 v[188:191], v174 offset:1024
	ds_read_b128 v[192:195], v174 offset:2048
	ds_read_b128 v[196:199], v174 offset:3072
	ds_read_b128 v[200:203], v174 offset:4096
	ds_read_b128 v[218:221], v174 offset:5120
	ds_read_b128 v[222:225], v174 offset:6144
	ds_read_b128 v[226:229], v174 offset:7168
	global_load_lds_dwordx4 v160, s[26:27]
	s_add_i32 m0, s37, 0xe000
	s_nop 0
	global_load_lds_dwordx4 v162, s[26:27]
	s_cmp_lg_u32 s52, -2
	s_cbranch_scc1 .Lz_skip_3
	v_mov_b64_e32 v[0:1], 0
	v_mov_b64_e32 v[2:3], 0
	v_mov_b64_e32 v[32:33], 0
	v_mov_b64_e32 v[34:35], 0
	v_mov_b64_e32 v[4:5], 0
	v_mov_b64_e32 v[6:7], 0
	v_mov_b64_e32 v[36:37], 0
	v_mov_b64_e32 v[38:39], 0
	v_mov_b64_e32 v[8:9], 0
	v_mov_b64_e32 v[10:11], 0
	v_mov_b64_e32 v[40:41], 0
	v_mov_b64_e32 v[42:43], 0
	v_mov_b64_e32 v[12:13], 0
	v_mov_b64_e32 v[14:15], 0
	v_mov_b64_e32 v[44:45], 0
	v_mov_b64_e32 v[46:47], 0
	v_mov_b64_e32 v[64:65], 0
	v_mov_b64_e32 v[66:67], 0
	v_mov_b64_e32 v[96:97], 0
	v_mov_b64_e32 v[98:99], 0
	v_mov_b64_e32 v[68:69], 0
	v_mov_b64_e32 v[70:71], 0
	v_mov_b64_e32 v[100:101], 0
	v_mov_b64_e32 v[102:103], 0
	v_mov_b64_e32 v[72:73], 0
	v_mov_b64_e32 v[74:75], 0
	v_mov_b64_e32 v[104:105], 0
	v_mov_b64_e32 v[106:107], 0
	v_mov_b64_e32 v[76:77], 0
	v_mov_b64_e32 v[78:79], 0
	v_mov_b64_e32 v[108:109], 0
	v_mov_b64_e32 v[110:111], 0
	v_mov_b64_e32 v[16:17], 0
	v_mov_b64_e32 v[18:19], 0
	v_mov_b64_e32 v[48:49], 0
	v_mov_b64_e32 v[50:51], 0
	v_mov_b64_e32 v[20:21], 0
	v_mov_b64_e32 v[22:23], 0
	v_mov_b64_e32 v[52:53], 0
	v_mov_b64_e32 v[54:55], 0
	v_mov_b64_e32 v[24:25], 0
	v_mov_b64_e32 v[26:27], 0
	v_mov_b64_e32 v[56:57], 0
	v_mov_b64_e32 v[58:59], 0
	v_mov_b64_e32 v[28:29], 0
	v_mov_b64_e32 v[30:31], 0
	v_mov_b64_e32 v[60:61], 0
	v_mov_b64_e32 v[62:63], 0
	v_mov_b64_e32 v[80:81], 0
	v_mov_b64_e32 v[82:83], 0
	v_mov_b64_e32 v[112:113], 0
	v_mov_b64_e32 v[114:115], 0
	v_mov_b64_e32 v[84:85], 0
	v_mov_b64_e32 v[86:87], 0
	v_mov_b64_e32 v[116:117], 0
	v_mov_b64_e32 v[118:119], 0
	v_mov_b64_e32 v[88:89], 0
	v_mov_b64_e32 v[90:91], 0
	v_mov_b64_e32 v[120:121], 0
	v_mov_b64_e32 v[122:123], 0
	v_mov_b64_e32 v[92:93], 0
	v_mov_b64_e32 v[94:95], 0
	v_mov_b64_e32 v[124:125], 0
	v_mov_b64_e32 v[126:127], 0
.Lz_skip_3:
	s_waitcnt vmcnt(8)
	s_waitcnt lgkmcnt(0)
	s_barrier
	s_waitcnt lgkmcnt(0)
	v_mfma_f32_16x16x32_bf16 v[124:127], v[128:131], v[184:187], v[124:127]
	v_mfma_f32_16x16x32_bf16 v[92:95], v[136:139], v[184:187], v[92:95]
	v_mfma_f32_16x16x32_bf16 v[120:123], v[128:131], v[192:195], v[120:123]
	v_mfma_f32_16x16x32_bf16 v[88:91], v[136:139], v[192:195], v[88:91]
	v_mfma_f32_16x16x32_bf16 v[116:119], v[128:131], v[200:203], v[116:119]
	v_mfma_f32_16x16x32_bf16 v[84:87], v[136:139], v[200:203], v[84:87]
	v_mfma_f32_16x16x32_bf16 v[112:115], v[128:131], v[222:225], v[112:115]
	v_mfma_f32_16x16x32_bf16 v[80:83], v[136:139], v[222:225], v[80:83]
	v_mfma_f32_16x16x32_bf16 v[124:127], v[132:135], v[188:191], v[124:127]
	v_mfma_f32_16x16x32_bf16 v[92:95], v[140:143], v[188:191], v[92:95]
	v_mfma_f32_16x16x32_bf16 v[120:123], v[132:135], v[196:199], v[120:123]
	v_mfma_f32_16x16x32_bf16 v[88:91], v[140:143], v[196:199], v[88:91]
	v_mfma_f32_16x16x32_bf16 v[116:119], v[132:135], v[218:221], v[116:119]
	v_mfma_f32_16x16x32_bf16 v[84:87], v[140:143], v[218:221], v[84:87]
	v_mfma_f32_16x16x32_bf16 v[112:115], v[132:135], v[226:229], v[112:115]
	v_mfma_f32_16x16x32_bf16 v[80:83], v[140:143], v[226:229], v[80:83]
	v_mfma_f32_16x16x32_bf16 v[60:63], v[164:167], v[184:187], v[60:63]
	v_mfma_f32_16x16x32_bf16 v[28:31], v[176:179], v[184:187], v[28:31]
	v_mfma_f32_16x16x32_bf16 v[56:59], v[164:167], v[192:195], v[56:59]
	v_mfma_f32_16x16x32_bf16 v[24:27], v[176:179], v[192:195], v[24:27]
	v_mfma_f32_16x16x32_bf16 v[52:55], v[164:167], v[200:203], v[52:55]
	v_mfma_f32_16x16x32_bf16 v[20:23], v[176:179], v[200:203], v[20:23]
	v_mfma_f32_16x16x32_bf16 v[48:51], v[164:167], v[222:225], v[48:51]
	v_mfma_f32_16x16x32_bf16 v[16:19], v[176:179], v[222:225], v[16:19]
	v_mfma_f32_16x16x32_bf16 v[60:63], v[168:171], v[188:191], v[60:63]
	v_mfma_f32_16x16x32_bf16 v[28:31], v[180:183], v[188:191], v[28:31]
	v_mfma_f32_16x16x32_bf16 v[56:59], v[168:171], v[196:199], v[56:59]
	v_mfma_f32_16x16x32_bf16 v[24:27], v[180:183], v[196:199], v[24:27]
	v_mfma_f32_16x16x32_bf16 v[52:55], v[168:171], v[218:221], v[52:55]
	v_mfma_f32_16x16x32_bf16 v[20:23], v[180:183], v[218:221], v[20:23]
	v_mfma_f32_16x16x32_bf16 v[48:51], v[168:171], v[226:229], v[48:51]
	v_mfma_f32_16x16x32_bf16 v[16:19], v[180:183], v[226:229], v[16:19]
	s_barrier
	s_add_i32 s53, s53, s36
	v_lshl_add_u64 v[154:155], s[30:31], 0, v[158:159]
	s_mov_b32 m0, s53
	ds_read_b128 v[184:187], v174 offset:16384
	ds_read_b128 v[188:191], v174 offset:17408
	ds_read_b128 v[192:195], v174 offset:18432
	ds_read_b128 v[196:199], v174 offset:19456
	ds_read_b128 v[200:203], v174 offset:20480
	ds_read_b128 v[218:221], v174 offset:21504
	ds_read_b128 v[222:225], v174 offset:22528
	ds_read_b128 v[226:229], v174 offset:23552
	global_load_lds_dwordx4 v[154:155], off
	s_add_i32 m0, s53, 0x2000
	s_add_u32 s54, s30, 0x40000
	v_lshl_add_u64 v[156:157], s[30:31], 0, v[144:145]
	s_addc_u32 s55, s31, 0
	s_add_i32 s53, s56, s36
	global_load_lds_dwordx4 v[156:157], off
	s_mov_b32 m0, s53
	v_lshl_add_u64 v[212:213], s[34:35], 0, v[146:147]
	global_load_lds_dwordx4 v158, s[54:55]
	s_add_i32 m0, s53, 0x2000
	s_nop 0
	global_load_lds_dwordx4 v144, s[54:55]
	v_lshl_add_u64 v[204:205], s[34:35], 0, v[148:149]
	s_mov_b32 m0, s37
	s_nop 0
	global_load_lds_dwordx4 v[204:205], off
	s_mov_b32 m0, s38
	s_nop 0
	global_load_lds_dwordx4 v[212:213], off
	s_waitcnt vmcnt(8)
	s_waitcnt lgkmcnt(0)
	s_barrier
	s_waitcnt lgkmcnt(0)
	v_mfma_f32_16x16x32_bf16 v[108:111], v[128:131], v[184:187], v[108:111]
	v_mfma_f32_16x16x32_bf16 v[76:79], v[136:139], v[184:187], v[76:79]
	v_mfma_f32_16x16x32_bf16 v[104:107], v[128:131], v[192:195], v[104:107]
	v_mfma_f32_16x16x32_bf16 v[72:75], v[136:139], v[192:195], v[72:75]
	v_mfma_f32_16x16x32_bf16 v[100:103], v[128:131], v[200:203], v[100:103]
	v_mfma_f32_16x16x32_bf16 v[68:71], v[136:139], v[200:203], v[68:71]
	v_mfma_f32_16x16x32_bf16 v[96:99], v[128:131], v[222:225], v[96:99]
	v_mfma_f32_16x16x32_bf16 v[64:67], v[136:139], v[222:225], v[64:67]
	v_mfma_f32_16x16x32_bf16 v[108:111], v[132:135], v[188:191], v[108:111]
	v_mfma_f32_16x16x32_bf16 v[76:79], v[140:143], v[188:191], v[76:79]
	v_mfma_f32_16x16x32_bf16 v[104:107], v[132:135], v[196:199], v[104:107]
	v_mfma_f32_16x16x32_bf16 v[72:75], v[140:143], v[196:199], v[72:75]
	v_mfma_f32_16x16x32_bf16 v[100:103], v[132:135], v[218:221], v[100:103]
	v_mfma_f32_16x16x32_bf16 v[68:71], v[140:143], v[218:221], v[68:71]
	v_mfma_f32_16x16x32_bf16 v[96:99], v[132:135], v[226:229], v[96:99]
	v_mfma_f32_16x16x32_bf16 v[64:67], v[140:143], v[226:229], v[64:67]
	v_mfma_f32_16x16x32_bf16 v[44:47], v[164:167], v[184:187], v[44:47]
	v_mfma_f32_16x16x32_bf16 v[12:15], v[176:179], v[184:187], v[12:15]
	v_mfma_f32_16x16x32_bf16 v[40:43], v[164:167], v[192:195], v[40:43]
	v_mfma_f32_16x16x32_bf16 v[8:11], v[176:179], v[192:195], v[8:11]
	v_mfma_f32_16x16x32_bf16 v[36:39], v[164:167], v[200:203], v[36:39]
	v_mfma_f32_16x16x32_bf16 v[4:7], v[176:179], v[200:203], v[4:7]
	v_mfma_f32_16x16x32_bf16 v[32:35], v[164:167], v[222:225], v[32:35]
	v_mfma_f32_16x16x32_bf16 v[0:3], v[176:179], v[222:225], v[0:3]
	v_mfma_f32_16x16x32_bf16 v[44:47], v[168:171], v[188:191], v[44:47]
	v_mfma_f32_16x16x32_bf16 v[12:15], v[180:183], v[188:191], v[12:15]
	v_mfma_f32_16x16x32_bf16 v[40:43], v[168:171], v[196:199], v[40:43]
	v_mfma_f32_16x16x32_bf16 v[8:11], v[180:183], v[196:199], v[8:11]
	v_mfma_f32_16x16x32_bf16 v[36:39], v[168:171], v[218:221], v[36:39]
	v_mfma_f32_16x16x32_bf16 v[4:7], v[180:183], v[218:221], v[4:7]
	v_mfma_f32_16x16x32_bf16 v[32:35], v[168:171], v[226:229], v[32:35]
	v_mfma_f32_16x16x32_bf16 v[0:3], v[180:183], v[226:229], v[0:3]
	s_barrier
	s_add_i32 s53, 0, 0x18000
	s_add_i32 s54, 0, 0x1c000
	v_add_u32_e32 v140, s53, v173
	v_add_u32_e32 v150, s54, v173
	ds_read_b128 v[128:131], v140
	ds_read_b128 v[132:135], v140 offset:1024
	ds_read_b128 v[136:139], v140 offset:2048
	ds_read_b128 v[140:143], v140 offset:3072
	ds_read_b128 v[164:167], v150
	ds_read_b128 v[168:171], v150 offset:1024
	ds_read_b128 v[176:179], v150 offset:2048
	ds_read_b128 v[180:183], v150 offset:3072
	s_add_u32 s34, s34, 0x40000
	s_addc_u32 s35, s35, 0
	s_mov_b32 m0, s39
	ds_read_b128 v[184:187], v174 offset:32768
	ds_read_b128 v[188:191], v174 offset:33792
	ds_read_b128 v[192:195], v174 offset:34816
	ds_read_b128 v[196:199], v174 offset:35840
	ds_read_b128 v[200:203], v174 offset:36864
	ds_read_b128 v[218:221], v174 offset:37888
	ds_read_b128 v[222:225], v174 offset:38912
	ds_read_b128 v[226:229], v174 offset:39936
	global_load_lds_dwordx4 v148, s[34:35]
	s_mov_b32 m0, s40
	s_nop 0
	global_load_lds_dwordx4 v146, s[34:35]
	s_waitcnt vmcnt(8)
	s_waitcnt lgkmcnt(0)
	s_barrier
	s_waitcnt lgkmcnt(0)
	v_mfma_f32_16x16x32_bf16 v[124:127], v[128:131], v[184:187], v[124:127]
	v_mfma_f32_16x16x32_bf16 v[92:95], v[136:139], v[184:187], v[92:95]
	v_mfma_f32_16x16x32_bf16 v[120:123], v[128:131], v[192:195], v[120:123]
	v_mfma_f32_16x16x32_bf16 v[88:91], v[136:139], v[192:195], v[88:91]
	v_mfma_f32_16x16x32_bf16 v[116:119], v[128:131], v[200:203], v[116:119]
	v_mfma_f32_16x16x32_bf16 v[84:87], v[136:139], v[200:203], v[84:87]
	v_mfma_f32_16x16x32_bf16 v[112:115], v[128:131], v[222:225], v[112:115]
	v_mfma_f32_16x16x32_bf16 v[80:83], v[136:139], v[222:225], v[80:83]
	v_mfma_f32_16x16x32_bf16 v[124:127], v[132:135], v[188:191], v[124:127]
	v_mfma_f32_16x16x32_bf16 v[92:95], v[140:143], v[188:191], v[92:95]
	v_mfma_f32_16x16x32_bf16 v[120:123], v[132:135], v[196:199], v[120:123]
	v_mfma_f32_16x16x32_bf16 v[88:91], v[140:143], v[196:199], v[88:91]
	v_mfma_f32_16x16x32_bf16 v[116:119], v[132:135], v[218:221], v[116:119]
	v_mfma_f32_16x16x32_bf16 v[84:87], v[140:143], v[218:221], v[84:87]
	v_mfma_f32_16x16x32_bf16 v[112:115], v[132:135], v[226:229], v[112:115]
	v_mfma_f32_16x16x32_bf16 v[80:83], v[140:143], v[226:229], v[80:83]
	v_mfma_f32_16x16x32_bf16 v[60:63], v[164:167], v[184:187], v[60:63]
	v_mfma_f32_16x16x32_bf16 v[28:31], v[176:179], v[184:187], v[28:31]
	v_mfma_f32_16x16x32_bf16 v[56:59], v[164:167], v[192:195], v[56:59]
	v_mfma_f32_16x16x32_bf16 v[24:27], v[176:179], v[192:195], v[24:27]
	v_mfma_f32_16x16x32_bf16 v[52:55], v[164:167], v[200:203], v[52:55]
	v_mfma_f32_16x16x32_bf16 v[20:23], v[176:179], v[200:203], v[20:23]
	v_mfma_f32_16x16x32_bf16 v[48:51], v[164:167], v[222:225], v[48:51]
	v_mfma_f32_16x16x32_bf16 v[16:19], v[176:179], v[222:225], v[16:19]
	v_mfma_f32_16x16x32_bf16 v[60:63], v[168:171], v[188:191], v[60:63]
	v_mfma_f32_16x16x32_bf16 v[28:31], v[180:183], v[188:191], v[28:31]
	v_mfma_f32_16x16x32_bf16 v[56:59], v[168:171], v[196:199], v[56:59]
	v_mfma_f32_16x16x32_bf16 v[24:27], v[180:183], v[196:199], v[24:27]
	v_mfma_f32_16x16x32_bf16 v[52:55], v[168:171], v[218:221], v[52:55]
	v_mfma_f32_16x16x32_bf16 v[20:23], v[180:183], v[218:221], v[20:23]
	v_mfma_f32_16x16x32_bf16 v[48:51], v[168:171], v[226:229], v[48:51]
	v_mfma_f32_16x16x32_bf16 v[16:19], v[180:183], v[226:229], v[16:19]
	s_barrier
	s_add_i32 s34, s53, s36
	v_lshl_add_u64 v[154:155], v[154:155], 0, s[28:29]
	s_mov_b32 m0, s34
	ds_read_b128 v[184:187], v174 offset:49152
	ds_read_b128 v[188:191], v174 offset:50176
	ds_read_b128 v[192:195], v174 offset:51200
	ds_read_b128 v[196:199], v174 offset:52224
	ds_read_b128 v[200:203], v174 offset:53248
	ds_read_b128 v[218:221], v174 offset:54272
	ds_read_b128 v[222:225], v174 offset:55296
	ds_read_b128 v[226:229], v174 offset:56320
	global_load_lds_dwordx4 v[154:155], off
	s_add_i32 m0, s34, 0x2000
	s_add_u32 s30, s30, 0x40080
	v_lshl_add_u64 v[154:155], v[156:157], 0, s[28:29]
	s_addc_u32 s31, s31, 0
	s_add_i32 s34, s54, s36
	global_load_lds_dwordx4 v[154:155], off
	s_mov_b32 m0, s34
	s_nop 0
	global_load_lds_dwordx4 v158, s[30:31]
	s_add_i32 m0, s34, 0x2000
	s_nop 0
	global_load_lds_dwordx4 v144, s[30:31]
	v_lshl_add_u64 v[154:155], v[204:205], 0, s[28:29]
	s_mov_b32 m0, s43
	s_nop 0
	global_load_lds_dwordx4 v[154:155], off
	v_lshl_add_u64 v[154:155], v[212:213], 0, s[28:29]
	s_mov_b32 m0, s44
	s_nop 0
	global_load_lds_dwordx4 v[154:155], off
	s_waitcnt vmcnt(8)
	s_waitcnt lgkmcnt(0)
	s_barrier
	s_waitcnt lgkmcnt(0)
	v_mfma_f32_16x16x32_bf16 v[108:111], v[128:131], v[184:187], v[108:111]
	v_mfma_f32_16x16x32_bf16 v[76:79], v[136:139], v[184:187], v[76:79]
	v_mfma_f32_16x16x32_bf16 v[104:107], v[128:131], v[192:195], v[104:107]
	v_mfma_f32_16x16x32_bf16 v[72:75], v[136:139], v[192:195], v[72:75]
	v_mfma_f32_16x16x32_bf16 v[100:103], v[128:131], v[200:203], v[100:103]
	v_mfma_f32_16x16x32_bf16 v[68:71], v[136:139], v[200:203], v[68:71]
	v_mfma_f32_16x16x32_bf16 v[96:99], v[128:131], v[222:225], v[96:99]
	v_mfma_f32_16x16x32_bf16 v[64:67], v[136:139], v[222:225], v[64:67]
	v_mfma_f32_16x16x32_bf16 v[108:111], v[132:135], v[188:191], v[108:111]
	v_mfma_f32_16x16x32_bf16 v[76:79], v[140:143], v[188:191], v[76:79]
	v_mfma_f32_16x16x32_bf16 v[104:107], v[132:135], v[196:199], v[104:107]
	v_mfma_f32_16x16x32_bf16 v[72:75], v[140:143], v[196:199], v[72:75]
	v_mfma_f32_16x16x32_bf16 v[100:103], v[132:135], v[218:221], v[100:103]
	v_mfma_f32_16x16x32_bf16 v[68:71], v[140:143], v[218:221], v[68:71]
	v_mfma_f32_16x16x32_bf16 v[96:99], v[132:135], v[226:229], v[96:99]
	v_mfma_f32_16x16x32_bf16 v[64:67], v[140:143], v[226:229], v[64:67]
	v_mfma_f32_16x16x32_bf16 v[44:47], v[164:167], v[184:187], v[44:47]
	v_mfma_f32_16x16x32_bf16 v[12:15], v[176:179], v[184:187], v[12:15]
	v_mfma_f32_16x16x32_bf16 v[40:43], v[164:167], v[192:195], v[40:43]
	v_mfma_f32_16x16x32_bf16 v[8:11], v[176:179], v[192:195], v[8:11]
	v_mfma_f32_16x16x32_bf16 v[36:39], v[164:167], v[200:203], v[36:39]
	v_mfma_f32_16x16x32_bf16 v[4:7], v[176:179], v[200:203], v[4:7]
	v_mfma_f32_16x16x32_bf16 v[32:35], v[164:167], v[222:225], v[32:35]
	v_mfma_f32_16x16x32_bf16 v[0:3], v[176:179], v[222:225], v[0:3]
	v_mfma_f32_16x16x32_bf16 v[44:47], v[168:171], v[188:191], v[44:47]
	v_mfma_f32_16x16x32_bf16 v[12:15], v[180:183], v[188:191], v[12:15]
	v_mfma_f32_16x16x32_bf16 v[40:43], v[168:171], v[196:199], v[40:43]
	v_mfma_f32_16x16x32_bf16 v[8:11], v[180:183], v[196:199], v[8:11]
	v_mfma_f32_16x16x32_bf16 v[36:39], v[168:171], v[218:221], v[36:39]
	v_mfma_f32_16x16x32_bf16 v[4:7], v[180:183], v[218:221], v[4:7]
	v_mfma_f32_16x16x32_bf16 v[32:35], v[168:171], v[226:229], v[32:35]
	v_mfma_f32_16x16x32_bf16 v[0:3], v[180:183], v[226:229], v[0:3]
	s_barrier
	s_add_i32 s52, s52, 2
	s_add_u32 s26, s26, 0x100
	s_addc_u32 s27, s27, 0
	s_add_u32 s50, s50, 0x100
	s_addc_u32 s51, s51, 0
	s_cmp_gt_u32 s52, 13
	s_cbranch_scc0 .LBB0_764
	s_and_b64 vcc, exec, s[16:17]
	s_mov_b32 s49, s57
	s_cbranch_vccz .LBB0_767
	s_barrier

.LBB0_1335:
	s_add_u32 s22, s8, 0xfffe0080
	s_addc_u32 s23, s9, -1
	s_add_i32 s54, 0, 0x10000
	s_cmp_eq_u32 s53, 4
	s_cselect_b32 s25, s17, s23
	s_cselect_b32 s24, s49, s22
	v_add_u32_e32 v146, s54, v158
	s_cselect_b32 s23, s15, s52
	s_cselect_b32 s22, s50, s51
	s_add_i32 s56, 0, 0x14000
	ds_read_b128 v[138:141], v146
	ds_read_b128 v[142:145], v146 offset:1024
	ds_read_b128 v[154:157], v146 offset:2048
	ds_read_b128 v[160:163], v146 offset:3072
	v_add_u32_e32 v146, s56, v158
	ds_read_b128 v[164:167], v146
	ds_read_b128 v[168:171], v146 offset:1024
	ds_read_b128 v[172:175], v146 offset:2048
	ds_read_b128 v[176:179], v146 offset:3072
	s_add_i32 m0, s38, 0xc000
	ds_read_b128 v[180:183], v159
	ds_read_b128 v[184:187], v159 offset:1024
	ds_read_b128 v[188:191], v159 offset:2048
	ds_read_b128 v[192:195], v159 offset:3072
	ds_read_b128 v[196:199], v159 offset:4096
	ds_read_b128 v[200:203], v159 offset:5120
	ds_read_b128 v[212:215], v159 offset:6144
	ds_read_b128 v[220:223], v159 offset:7168
	global_load_lds_dwordx4 v134, s[8:9]
	s_add_i32 m0, s38, 0xe000
	s_nop 0
	global_load_lds_dwordx4 v136, s[8:9]
	s_cmp_lg_u32 s53, -2
	s_cbranch_scc1 .Lz_skip_4
	v_mov_b64_e32 v[0:1], 0
	v_mov_b64_e32 v[2:3], 0
	v_mov_b64_e32 v[4:5], 0
	v_mov_b64_e32 v[6:7], 0
	v_mov_b64_e32 v[16:17], 0
	v_mov_b64_e32 v[18:19], 0
	v_mov_b64_e32 v[20:21], 0
	v_mov_b64_e32 v[22:23], 0
	v_mov_b64_e32 v[32:33], 0
	v_mov_b64_e32 v[34:35], 0
	v_mov_b64_e32 v[36:37], 0
	v_mov_b64_e32 v[38:39], 0
	v_mov_b64_e32 v[48:49], 0
	v_mov_b64_e32 v[50:51], 0
	v_mov_b64_e32 v[52:53], 0
	v_mov_b64_e32 v[54:55], 0
	v_mov_b64_e32 v[8:9], 0
	v_mov_b64_e32 v[10:11], 0
	v_mov_b64_e32 v[12:13], 0
	v_mov_b64_e32 v[14:15], 0
	v_mov_b64_e32 v[24:25], 0
	v_mov_b64_e32 v[26:27], 0
	v_mov_b64_e32 v[28:29], 0
	v_mov_b64_e32 v[30:31], 0
	v_mov_b64_e32 v[40:41], 0
	v_mov_b64_e32 v[42:43], 0
	v_mov_b64_e32 v[44:45], 0
	v_mov_b64_e32 v[46:47], 0
	v_mov_b64_e32 v[56:57], 0
	v_mov_b64_e32 v[58:59], 0
	v_mov_b64_e32 v[60:61], 0
	v_mov_b64_e32 v[62:63], 0
	v_mov_b64_e32 v[64:65], 0
	v_mov_b64_e32 v[66:67], 0
	v_mov_b64_e32 v[68:69], 0
	v_mov_b64_e32 v[70:71], 0
	v_mov_b64_e32 v[80:81], 0
	v_mov_b64_e32 v[82:83], 0
	v_mov_b64_e32 v[84:85], 0
	v_mov_b64_e32 v[86:87], 0
	v_mov_b64_e32 v[96:97], 0
	v_mov_b64_e32 v[98:99], 0
	v_mov_b64_e32 v[100:101], 0
	v_mov_b64_e32 v[102:103], 0
	v_mov_b64_e32 v[112:113], 0
	v_mov_b64_e32 v[114:115], 0
	v_mov_b64_e32 v[116:117], 0
	v_mov_b64_e32 v[118:119], 0
	v_mov_b64_e32 v[72:73], 0
	v_mov_b64_e32 v[74:75], 0
	v_mov_b64_e32 v[76:77], 0
	v_mov_b64_e32 v[78:79], 0
	v_mov_b64_e32 v[88:89], 0
	v_mov_b64_e32 v[90:91], 0
	v_mov_b64_e32 v[92:93], 0
	v_mov_b64_e32 v[94:95], 0
	v_mov_b64_e32 v[104:105], 0
	v_mov_b64_e32 v[106:107], 0
	v_mov_b64_e32 v[108:109], 0
	v_mov_b64_e32 v[110:111], 0
	v_mov_b64_e32 v[120:121], 0
	v_mov_b64_e32 v[122:123], 0
	v_mov_b64_e32 v[124:125], 0
	v_mov_b64_e32 v[126:127], 0
.Lz_skip_4:
	s_waitcnt vmcnt(8)
	s_waitcnt lgkmcnt(0)
	s_barrier
	s_waitcnt lgkmcnt(0)
	v_mfma_f32_16x16x32_bf16 v[124:127], v[138:141], v[180:183], v[124:127]
	v_mfma_f32_16x16x32_bf16 v[120:123], v[154:157], v[180:183], v[120:123]
	v_mfma_f32_16x16x32_bf16 v[108:111], v[138:141], v[188:191], v[108:111]
	v_mfma_f32_16x16x32_bf16 v[104:107], v[154:157], v[188:191], v[104:107]
	v_mfma_f32_16x16x32_bf16 v[92:95], v[138:141], v[196:199], v[92:95]
	v_mfma_f32_16x16x32_bf16 v[88:91], v[154:157], v[196:199], v[88:91]
	v_mfma_f32_16x16x32_bf16 v[76:79], v[138:141], v[212:215], v[76:79]
	v_mfma_f32_16x16x32_bf16 v[72:75], v[154:157], v[212:215], v[72:75]
	v_mfma_f32_16x16x32_bf16 v[124:127], v[142:145], v[184:187], v[124:127]
	v_mfma_f32_16x16x32_bf16 v[120:123], v[160:163], v[184:187], v[120:123]
	v_mfma_f32_16x16x32_bf16 v[108:111], v[142:145], v[192:195], v[108:111]
	v_mfma_f32_16x16x32_bf16 v[104:107], v[160:163], v[192:195], v[104:107]
	v_mfma_f32_16x16x32_bf16 v[92:95], v[142:145], v[200:203], v[92:95]
	v_mfma_f32_16x16x32_bf16 v[88:91], v[160:163], v[200:203], v[88:91]
	v_mfma_f32_16x16x32_bf16 v[76:79], v[142:145], v[220:223], v[76:79]
	v_mfma_f32_16x16x32_bf16 v[72:75], v[160:163], v[220:223], v[72:75]
	v_mfma_f32_16x16x32_bf16 v[116:119], v[164:167], v[180:183], v[116:119]
	v_mfma_f32_16x16x32_bf16 v[112:115], v[172:175], v[180:183], v[112:115]
	v_mfma_f32_16x16x32_bf16 v[100:103], v[164:167], v[188:191], v[100:103]
	v_mfma_f32_16x16x32_bf16 v[96:99], v[172:175], v[188:191], v[96:99]
	v_mfma_f32_16x16x32_bf16 v[84:87], v[164:167], v[196:199], v[84:87]
	v_mfma_f32_16x16x32_bf16 v[80:83], v[172:175], v[196:199], v[80:83]
	v_mfma_f32_16x16x32_bf16 v[68:71], v[164:167], v[212:215], v[68:71]
	v_mfma_f32_16x16x32_bf16 v[64:67], v[172:175], v[212:215], v[64:67]
	v_mfma_f32_16x16x32_bf16 v[116:119], v[168:171], v[184:187], v[116:119]
	v_mfma_f32_16x16x32_bf16 v[112:115], v[176:179], v[184:187], v[112:115]
	v_mfma_f32_16x16x32_bf16 v[100:103], v[168:171], v[192:195], v[100:103]
	v_mfma_f32_16x16x32_bf16 v[96:99], v[176:179], v[192:195], v[96:99]
	v_mfma_f32_16x16x32_bf16 v[84:87], v[168:171], v[200:203], v[84:87]
	v_mfma_f32_16x16x32_bf16 v[80:83], v[176:179], v[200:203], v[80:83]
	v_mfma_f32_16x16x32_bf16 v[68:71], v[168:171], v[220:223], v[68:71]
	v_mfma_f32_16x16x32_bf16 v[64:67], v[176:179], v[220:223], v[64:67]
	s_barrier
	s_add_i32 s54, s54, s37
	v_lshl_add_u64 v[146:147], s[22:23], 0, v[148:149]
	s_mov_b32 m0, s54
	ds_read_b128 v[180:183], v159 offset:16384
	ds_read_b128 v[184:187], v159 offset:17408
	ds_read_b128 v[188:191], v159 offset:18432
	ds_read_b128 v[192:195], v159 offset:19456
	ds_read_b128 v[196:199], v159 offset:20480
	ds_read_b128 v[200:203], v159 offset:21504
	ds_read_b128 v[212:215], v159 offset:22528
	ds_read_b128 v[220:223], v159 offset:23552
	global_load_lds_dwordx4 v[146:147], off
	s_add_i32 m0, s54, 0x2000
	s_add_u32 s54, s22, 0x20000
	v_lshl_add_u64 v[150:151], s[22:23], 0, v[128:129]
	s_addc_u32 s55, s23, 0
	s_add_i32 s56, s56, s37
	global_load_lds_dwordx4 v[150:151], off
	s_mov_b32 m0, s56
	v_lshl_add_u64 v[204:205], s[24:25], 0, v[130:131]
	global_load_lds_dwordx4 v148, s[54:55]
	s_add_i32 m0, s56, 0x2000
	s_nop 0
	global_load_lds_dwordx4 v128, s[54:55]
	v_lshl_add_u64 v[152:153], s[24:25], 0, v[132:133]
	s_mov_b32 m0, s38
	s_nop 0
	global_load_lds_dwordx4 v[152:153], off
	s_mov_b32 m0, s39
	s_nop 0
	global_load_lds_dwordx4 v[204:205], off
	s_waitcnt vmcnt(8)
	s_waitcnt lgkmcnt(0)
	s_barrier
	s_waitcnt lgkmcnt(0)
	v_mfma_f32_16x16x32_bf16 v[60:63], v[138:141], v[180:183], v[60:63]
	v_mfma_f32_16x16x32_bf16 v[56:59], v[154:157], v[180:183], v[56:59]
	v_mfma_f32_16x16x32_bf16 v[44:47], v[138:141], v[188:191], v[44:47]
	v_mfma_f32_16x16x32_bf16 v[40:43], v[154:157], v[188:191], v[40:43]
	v_mfma_f32_16x16x32_bf16 v[28:31], v[138:141], v[196:199], v[28:31]
	v_mfma_f32_16x16x32_bf16 v[24:27], v[154:157], v[196:199], v[24:27]
	v_mfma_f32_16x16x32_bf16 v[12:15], v[138:141], v[212:215], v[12:15]
	v_mfma_f32_16x16x32_bf16 v[8:11], v[154:157], v[212:215], v[8:11]
	v_mfma_f32_16x16x32_bf16 v[60:63], v[142:145], v[184:187], v[60:63]
	v_mfma_f32_16x16x32_bf16 v[56:59], v[160:163], v[184:187], v[56:59]
	v_mfma_f32_16x16x32_bf16 v[44:47], v[142:145], v[192:195], v[44:47]
	v_mfma_f32_16x16x32_bf16 v[40:43], v[160:163], v[192:195], v[40:43]
	v_mfma_f32_16x16x32_bf16 v[28:31], v[142:145], v[200:203], v[28:31]
	v_mfma_f32_16x16x32_bf16 v[24:27], v[160:163], v[200:203], v[24:27]
	v_mfma_f32_16x16x32_bf16 v[12:15], v[142:145], v[220:223], v[12:15]
	v_mfma_f32_16x16x32_bf16 v[8:11], v[160:163], v[220:223], v[8:11]
	v_mfma_f32_16x16x32_bf16 v[52:55], v[164:167], v[180:183], v[52:55]
	v_mfma_f32_16x16x32_bf16 v[48:51], v[172:175], v[180:183], v[48:51]
	v_mfma_f32_16x16x32_bf16 v[36:39], v[164:167], v[188:191], v[36:39]
	v_mfma_f32_16x16x32_bf16 v[32:35], v[172:175], v[188:191], v[32:35]
	v_mfma_f32_16x16x32_bf16 v[20:23], v[164:167], v[196:199], v[20:23]
	v_mfma_f32_16x16x32_bf16 v[16:19], v[172:175], v[196:199], v[16:19]
	v_mfma_f32_16x16x32_bf16 v[4:7], v[164:167], v[212:215], v[4:7]
	v_mfma_f32_16x16x32_bf16 v[0:3], v[172:175], v[212:215], v[0:3]
	v_mfma_f32_16x16x32_bf16 v[52:55], v[168:171], v[184:187], v[52:55]
	v_mfma_f32_16x16x32_bf16 v[48:51], v[176:179], v[184:187], v[48:51]
	v_mfma_f32_16x16x32_bf16 v[36:39], v[168:171], v[192:195], v[36:39]
	v_mfma_f32_16x16x32_bf16 v[32:35], v[176:179], v[192:195], v[32:35]
	v_mfma_f32_16x16x32_bf16 v[20:23], v[168:171], v[200:203], v[20:23]
	v_mfma_f32_16x16x32_bf16 v[16:19], v[176:179], v[200:203], v[16:19]
	v_mfma_f32_16x16x32_bf16 v[4:7], v[168:171], v[220:223], v[4:7]
	v_mfma_f32_16x16x32_bf16 v[0:3], v[176:179], v[220:223], v[0:3]
	s_barrier
	s_add_i32 s54, 0, 0x18000
	s_add_i32 s55, 0, 0x1c000
	v_add_u32_e32 v160, s54, v158
	v_add_u32_e32 v176, s55, v158
	ds_read_b128 v[138:141], v160
	ds_read_b128 v[142:145], v160 offset:1024
	ds_read_b128 v[154:157], v160 offset:2048
	ds_read_b128 v[160:163], v160 offset:3072
	ds_read_b128 v[164:167], v176
	ds_read_b128 v[168:171], v176 offset:1024
	ds_read_b128 v[172:175], v176 offset:2048
	ds_read_b128 v[176:179], v176 offset:3072
	s_add_u32 s24, s24, 0x20000
	s_addc_u32 s25, s25, 0
	s_mov_b32 m0, s40
	ds_read_b128 v[180:183], v159 offset:32768
	ds_read_b128 v[184:187], v159 offset:33792
	ds_read_b128 v[188:191], v159 offset:34816
	ds_read_b128 v[192:195], v159 offset:35840
	ds_read_b128 v[196:199], v159 offset:36864
	ds_read_b128 v[200:203], v159 offset:37888
	ds_read_b128 v[212:215], v159 offset:38912
	ds_read_b128 v[220:223], v159 offset:39936
	global_load_lds_dwordx4 v132, s[24:25]
	s_mov_b32 m0, s41
	s_nop 0
	global_load_lds_dwordx4 v130, s[24:25]
	s_waitcnt vmcnt(8)
	s_waitcnt lgkmcnt(0)
	s_barrier
	s_waitcnt lgkmcnt(0)
	v_mfma_f32_16x16x32_bf16 v[124:127], v[138:141], v[180:183], v[124:127]
	v_mfma_f32_16x16x32_bf16 v[120:123], v[154:157], v[180:183], v[120:123]
	v_mfma_f32_16x16x32_bf16 v[108:111], v[138:141], v[188:191], v[108:111]
	v_mfma_f32_16x16x32_bf16 v[104:107], v[154:157], v[188:191], v[104:107]
	v_mfma_f32_16x16x32_bf16 v[92:95], v[138:141], v[196:199], v[92:95]
	v_mfma_f32_16x16x32_bf16 v[88:91], v[154:157], v[196:199], v[88:91]
	v_mfma_f32_16x16x32_bf16 v[76:79], v[138:141], v[212:215], v[76:79]
	v_mfma_f32_16x16x32_bf16 v[72:75], v[154:157], v[212:215], v[72:75]
	v_mfma_f32_16x16x32_bf16 v[124:127], v[142:145], v[184:187], v[124:127]
	v_mfma_f32_16x16x32_bf16 v[120:123], v[160:163], v[184:187], v[120:123]
	v_mfma_f32_16x16x32_bf16 v[108:111], v[142:145], v[192:195], v[108:111]
	v_mfma_f32_16x16x32_bf16 v[104:107], v[160:163], v[192:195], v[104:107]
	v_mfma_f32_16x16x32_bf16 v[92:95], v[142:145], v[200:203], v[92:95]
	v_mfma_f32_16x16x32_bf16 v[88:91], v[160:163], v[200:203], v[88:91]
	v_mfma_f32_16x16x32_bf16 v[76:79], v[142:145], v[220:223], v[76:79]
	v_mfma_f32_16x16x32_bf16 v[72:75], v[160:163], v[220:223], v[72:75]
	v_mfma_f32_16x16x32_bf16 v[116:119], v[164:167], v[180:183], v[116:119]
	v_mfma_f32_16x16x32_bf16 v[112:115], v[172:175], v[180:183], v[112:115]
	v_mfma_f32_16x16x32_bf16 v[100:103], v[164:167], v[188:191], v[100:103]
	v_mfma_f32_16x16x32_bf16 v[96:99], v[172:175], v[188:191], v[96:99]
	v_mfma_f32_16x16x32_bf16 v[84:87], v[164:167], v[196:199], v[84:87]
	v_mfma_f32_16x16x32_bf16 v[80:83], v[172:175], v[196:199], v[80:83]
	v_mfma_f32_16x16x32_bf16 v[68:71], v[164:167], v[212:215], v[68:71]
	v_mfma_f32_16x16x32_bf16 v[64:67], v[172:175], v[212:215], v[64:67]
	v_mfma_f32_16x16x32_bf16 v[116:119], v[168:171], v[184:187], v[116:119]
	v_mfma_f32_16x16x32_bf16 v[112:115], v[176:179], v[184:187], v[112:115]
	v_mfma_f32_16x16x32_bf16 v[100:103], v[168:171], v[192:195], v[100:103]
	v_mfma_f32_16x16x32_bf16 v[96:99], v[176:179], v[192:195], v[96:99]
	v_mfma_f32_16x16x32_bf16 v[84:87], v[168:171], v[200:203], v[84:87]
	v_mfma_f32_16x16x32_bf16 v[80:83], v[176:179], v[200:203], v[80:83]
	v_mfma_f32_16x16x32_bf16 v[68:71], v[168:171], v[220:223], v[68:71]
	v_mfma_f32_16x16x32_bf16 v[64:67], v[176:179], v[220:223], v[64:67]
	s_barrier
	s_add_i32 s24, s54, s37
	v_lshl_add_u64 v[146:147], v[146:147], 0, s[28:29]
	s_mov_b32 m0, s24
	ds_read_b128 v[180:183], v159 offset:49152
	ds_read_b128 v[184:187], v159 offset:50176
	ds_read_b128 v[188:191], v159 offset:51200
	ds_read_b128 v[192:195], v159 offset:52224
	ds_read_b128 v[196:199], v159 offset:53248
	ds_read_b128 v[200:203], v159 offset:54272
	ds_read_b128 v[212:215], v159 offset:55296
	ds_read_b128 v[220:223], v159 offset:56320
	global_load_lds_dwordx4 v[146:147], off
	s_add_i32 m0, s24, 0x2000
	s_add_u32 s22, s22, 0x20080
	v_lshl_add_u64 v[146:147], v[150:151], 0, s[28:29]
	s_addc_u32 s23, s23, 0
	s_add_i32 s24, s55, s37
	global_load_lds_dwordx4 v[146:147], off
	s_mov_b32 m0, s24
	s_nop 0
	global_load_lds_dwordx4 v148, s[22:23]
	s_add_i32 m0, s24, 0x2000
	s_nop 0
	global_load_lds_dwordx4 v128, s[22:23]
	v_lshl_add_u64 v[146:147], v[152:153], 0, s[28:29]
	s_mov_b32 m0, s45
	s_nop 0
	global_load_lds_dwordx4 v[146:147], off
	v_lshl_add_u64 v[146:147], v[204:205], 0, s[28:29]
	s_mov_b32 m0, s46
	s_nop 0
	global_load_lds_dwordx4 v[146:147], off
	s_waitcnt vmcnt(8)
	s_waitcnt lgkmcnt(0)
	s_barrier
	s_waitcnt lgkmcnt(0)
	v_mfma_f32_16x16x32_bf16 v[60:63], v[138:141], v[180:183], v[60:63]
	v_mfma_f32_16x16x32_bf16 v[56:59], v[154:157], v[180:183], v[56:59]
	v_mfma_f32_16x16x32_bf16 v[44:47], v[138:141], v[188:191], v[44:47]
	v_mfma_f32_16x16x32_bf16 v[40:43], v[154:157], v[188:191], v[40:43]
	v_mfma_f32_16x16x32_bf16 v[28:31], v[138:141], v[196:199], v[28:31]
	v_mfma_f32_16x16x32_bf16 v[24:27], v[154:157], v[196:199], v[24:27]
	v_mfma_f32_16x16x32_bf16 v[12:15], v[138:141], v[212:215], v[12:15]
	v_mfma_f32_16x16x32_bf16 v[8:11], v[154:157], v[212:215], v[8:11]
	v_mfma_f32_16x16x32_bf16 v[60:63], v[142:145], v[184:187], v[60:63]
	v_mfma_f32_16x16x32_bf16 v[56:59], v[160:163], v[184:187], v[56:59]
	v_mfma_f32_16x16x32_bf16 v[44:47], v[142:145], v[192:195], v[44:47]
	v_mfma_f32_16x16x32_bf16 v[40:43], v[160:163], v[192:195], v[40:43]
	v_mfma_f32_16x16x32_bf16 v[28:31], v[142:145], v[200:203], v[28:31]
	v_mfma_f32_16x16x32_bf16 v[24:27], v[160:163], v[200:203], v[24:27]
	v_mfma_f32_16x16x32_bf16 v[12:15], v[142:145], v[220:223], v[12:15]
	v_mfma_f32_16x16x32_bf16 v[8:11], v[160:163], v[220:223], v[8:11]
	v_mfma_f32_16x16x32_bf16 v[52:55], v[164:167], v[180:183], v[52:55]
	v_mfma_f32_16x16x32_bf16 v[48:51], v[172:175], v[180:183], v[48:51]
	v_mfma_f32_16x16x32_bf16 v[36:39], v[164:167], v[188:191], v[36:39]
	v_mfma_f32_16x16x32_bf16 v[32:35], v[172:175], v[188:191], v[32:35]
	v_mfma_f32_16x16x32_bf16 v[20:23], v[164:167], v[196:199], v[20:23]
	v_mfma_f32_16x16x32_bf16 v[16:19], v[172:175], v[196:199], v[16:19]
	v_mfma_f32_16x16x32_bf16 v[4:7], v[164:167], v[212:215], v[4:7]
	v_mfma_f32_16x16x32_bf16 v[0:3], v[172:175], v[212:215], v[0:3]
	v_mfma_f32_16x16x32_bf16 v[52:55], v[168:171], v[184:187], v[52:55]
	v_mfma_f32_16x16x32_bf16 v[48:51], v[176:179], v[184:187], v[48:51]
	v_mfma_f32_16x16x32_bf16 v[36:39], v[168:171], v[192:195], v[36:39]
	v_mfma_f32_16x16x32_bf16 v[32:35], v[176:179], v[192:195], v[32:35]
	v_mfma_f32_16x16x32_bf16 v[20:23], v[168:171], v[200:203], v[20:23]
	v_mfma_f32_16x16x32_bf16 v[16:19], v[176:179], v[200:203], v[16:19]
	v_mfma_f32_16x16x32_bf16 v[4:7], v[168:171], v[220:223], v[4:7]
	v_mfma_f32_16x16x32_bf16 v[0:3], v[176:179], v[220:223], v[0:3]
	s_barrier
	s_add_i32 s53, s53, 2
	s_add_u32 s8, s8, 0x100
	s_addc_u32 s9, s9, 0
	s_add_u32 s51, s51, 0x100
	s_addc_u32 s52, s52, 0
	s_cmp_gt_u32 s53, 5
	s_cbranch_scc0 .LBB0_1335
	s_and_b64 vcc, exec, s[12:13]
	s_cbranch_vccz .LBB0_1338
	s_barrier

.LBB0_1438:
	s_add_u32 s20, s18, 0xfffc0080
	s_addc_u32 s21, s19, -1
	s_add_i32 s49, 0, 0x10000
	s_cmp_eq_u32 s48, 12
	s_cselect_b32 s23, s13, s21
	s_cselect_b32 s22, s44, s20
	v_add_u32_e32 v142, s49, v144
	s_cselect_b32 s21, s11, s47
	s_cselect_b32 s20, s45, s46
	s_add_i32 s52, 0, 0x14000
	ds_read_b128 v[138:141], v142
	ds_read_b128 v[154:157], v142 offset:1024
	ds_read_b128 v[158:161], v142 offset:2048
	ds_read_b128 v[162:165], v142 offset:3072
	v_add_u32_e32 v142, s52, v144
	ds_read_b128 v[166:169], v142
	ds_read_b128 v[170:173], v142 offset:1024
	ds_read_b128 v[174:177], v142 offset:2048
	ds_read_b128 v[178:181], v142 offset:3072
	s_add_i32 m0, s31, 0xc000
	ds_read_b128 v[182:185], v145
	ds_read_b128 v[186:189], v145 offset:1024
	ds_read_b128 v[190:193], v145 offset:2048
	ds_read_b128 v[194:197], v145 offset:3072
	ds_read_b128 v[198:201], v145 offset:4096
	ds_read_b128 v[202:205], v145 offset:5120
	ds_read_b128 v[212:215], v145 offset:6144
	ds_read_b128 v[220:223], v145 offset:7168
	global_load_lds_dwordx4 v134, s[18:19]
	s_add_i32 m0, s31, 0xe000
	s_nop 0
	global_load_lds_dwordx4 v136, s[18:19]
	s_cmp_lg_u32 s48, -2
	s_cbranch_scc1 .Lz_skip_5
	v_mov_b64_e32 v[0:1], 0
	v_mov_b64_e32 v[2:3], 0
	v_mov_b64_e32 v[4:5], 0
	v_mov_b64_e32 v[6:7], 0
	v_mov_b64_e32 v[16:17], 0
	v_mov_b64_e32 v[18:19], 0
	v_mov_b64_e32 v[20:21], 0
	v_mov_b64_e32 v[22:23], 0
	v_mov_b64_e32 v[32:33], 0
	v_mov_b64_e32 v[34:35], 0
	v_mov_b64_e32 v[36:37], 0
	v_mov_b64_e32 v[38:39], 0
	v_mov_b64_e32 v[48:49], 0
	v_mov_b64_e32 v[50:51], 0
	v_mov_b64_e32 v[52:53], 0
	v_mov_b64_e32 v[54:55], 0
	v_mov_b64_e32 v[8:9], 0
	v_mov_b64_e32 v[10:11], 0
	v_mov_b64_e32 v[12:13], 0
	v_mov_b64_e32 v[14:15], 0
	v_mov_b64_e32 v[24:25], 0
	v_mov_b64_e32 v[26:27], 0
	v_mov_b64_e32 v[28:29], 0
	v_mov_b64_e32 v[30:31], 0
	v_mov_b64_e32 v[40:41], 0
	v_mov_b64_e32 v[42:43], 0
	v_mov_b64_e32 v[44:45], 0
	v_mov_b64_e32 v[46:47], 0
	v_mov_b64_e32 v[56:57], 0
	v_mov_b64_e32 v[58:59], 0
	v_mov_b64_e32 v[60:61], 0
	v_mov_b64_e32 v[62:63], 0
	v_mov_b64_e32 v[64:65], 0
	v_mov_b64_e32 v[66:67], 0
	v_mov_b64_e32 v[68:69], 0
	v_mov_b64_e32 v[70:71], 0
	v_mov_b64_e32 v[80:81], 0
	v_mov_b64_e32 v[82:83], 0
	v_mov_b64_e32 v[84:85], 0
	v_mov_b64_e32 v[86:87], 0
	v_mov_b64_e32 v[96:97], 0
	v_mov_b64_e32 v[98:99], 0
	v_mov_b64_e32 v[100:101], 0
	v_mov_b64_e32 v[102:103], 0
	v_mov_b64_e32 v[112:113], 0
	v_mov_b64_e32 v[114:115], 0
	v_mov_b64_e32 v[116:117], 0
	v_mov_b64_e32 v[118:119], 0
	v_mov_b64_e32 v[72:73], 0
	v_mov_b64_e32 v[74:75], 0
	v_mov_b64_e32 v[76:77], 0
	v_mov_b64_e32 v[78:79], 0
	v_mov_b64_e32 v[88:89], 0
	v_mov_b64_e32 v[90:91], 0
	v_mov_b64_e32 v[92:93], 0
	v_mov_b64_e32 v[94:95], 0
	v_mov_b64_e32 v[104:105], 0
	v_mov_b64_e32 v[106:107], 0
	v_mov_b64_e32 v[108:109], 0
	v_mov_b64_e32 v[110:111], 0
	v_mov_b64_e32 v[120:121], 0
	v_mov_b64_e32 v[122:123], 0
	v_mov_b64_e32 v[124:125], 0
	v_mov_b64_e32 v[126:127], 0
.Lz_skip_5:
	s_waitcnt vmcnt(8)
	s_waitcnt lgkmcnt(0)
	s_barrier
	s_waitcnt lgkmcnt(0)
	v_mfma_f32_16x16x32_bf16 v[124:127], v[138:141], v[182:185], v[124:127]
	v_mfma_f32_16x16x32_bf16 v[120:123], v[158:161], v[182:185], v[120:123]
	v_mfma_f32_16x16x32_bf16 v[108:111], v[138:141], v[190:193], v[108:111]
	v_mfma_f32_16x16x32_bf16 v[104:107], v[158:161], v[190:193], v[104:107]
	v_mfma_f32_16x16x32_bf16 v[92:95], v[138:141], v[198:201], v[92:95]
	v_mfma_f32_16x16x32_bf16 v[88:91], v[158:161], v[198:201], v[88:91]
	v_mfma_f32_16x16x32_bf16 v[76:79], v[138:141], v[212:215], v[76:79]
	v_mfma_f32_16x16x32_bf16 v[72:75], v[158:161], v[212:215], v[72:75]
	v_mfma_f32_16x16x32_bf16 v[124:127], v[154:157], v[186:189], v[124:127]
	v_mfma_f32_16x16x32_bf16 v[120:123], v[162:165], v[186:189], v[120:123]
	v_mfma_f32_16x16x32_bf16 v[108:111], v[154:157], v[194:197], v[108:111]
	v_mfma_f32_16x16x32_bf16 v[104:107], v[162:165], v[194:197], v[104:107]
	v_mfma_f32_16x16x32_bf16 v[92:95], v[154:157], v[202:205], v[92:95]
	v_mfma_f32_16x16x32_bf16 v[88:91], v[162:165], v[202:205], v[88:91]
	v_mfma_f32_16x16x32_bf16 v[76:79], v[154:157], v[220:223], v[76:79]
	v_mfma_f32_16x16x32_bf16 v[72:75], v[162:165], v[220:223], v[72:75]
	v_mfma_f32_16x16x32_bf16 v[116:119], v[166:169], v[182:185], v[116:119]
	v_mfma_f32_16x16x32_bf16 v[112:115], v[174:177], v[182:185], v[112:115]
	v_mfma_f32_16x16x32_bf16 v[100:103], v[166:169], v[190:193], v[100:103]
	v_mfma_f32_16x16x32_bf16 v[96:99], v[174:177], v[190:193], v[96:99]
	v_mfma_f32_16x16x32_bf16 v[84:87], v[166:169], v[198:201], v[84:87]
	v_mfma_f32_16x16x32_bf16 v[80:83], v[174:177], v[198:201], v[80:83]
	v_mfma_f32_16x16x32_bf16 v[68:71], v[166:169], v[212:215], v[68:71]
	v_mfma_f32_16x16x32_bf16 v[64:67], v[174:177], v[212:215], v[64:67]
	v_mfma_f32_16x16x32_bf16 v[116:119], v[170:173], v[186:189], v[116:119]
	v_mfma_f32_16x16x32_bf16 v[112:115], v[178:181], v[186:189], v[112:115]
	v_mfma_f32_16x16x32_bf16 v[100:103], v[170:173], v[194:197], v[100:103]
	v_mfma_f32_16x16x32_bf16 v[96:99], v[178:181], v[194:197], v[96:99]
	v_mfma_f32_16x16x32_bf16 v[84:87], v[170:173], v[202:205], v[84:87]
	v_mfma_f32_16x16x32_bf16 v[80:83], v[178:181], v[202:205], v[80:83]
	v_mfma_f32_16x16x32_bf16 v[68:71], v[170:173], v[220:223], v[68:71]
	v_mfma_f32_16x16x32_bf16 v[64:67], v[178:181], v[220:223], v[64:67]
	s_barrier
	s_add_i32 s49, s49, s30
	v_lshl_add_u64 v[142:143], s[20:21], 0, v[148:149]
	s_mov_b32 m0, s49
	ds_read_b128 v[182:185], v145 offset:16384
	ds_read_b128 v[186:189], v145 offset:17408
	ds_read_b128 v[190:193], v145 offset:18432
	ds_read_b128 v[194:197], v145 offset:19456
	ds_read_b128 v[198:201], v145 offset:20480
	ds_read_b128 v[202:205], v145 offset:21504
	ds_read_b128 v[212:215], v145 offset:22528
	ds_read_b128 v[220:223], v145 offset:23552
	global_load_lds_dwordx4 v[142:143], off
	s_add_i32 m0, s49, 0x2000
	s_add_u32 s50, s20, 0x40000
	v_lshl_add_u64 v[146:147], s[20:21], 0, v[128:129]
	s_addc_u32 s51, s21, 0
	s_add_i32 s49, s52, s30
	global_load_lds_dwordx4 v[146:147], off
	s_mov_b32 m0, s49
	v_lshl_add_u64 v[152:153], s[22:23], 0, v[130:131]
	global_load_lds_dwordx4 v148, s[50:51]
	s_add_i32 m0, s49, 0x2000
	s_nop 0
	global_load_lds_dwordx4 v128, s[50:51]
	v_lshl_add_u64 v[150:151], s[22:23], 0, v[132:133]
	s_mov_b32 m0, s31
	s_nop 0
	global_load_lds_dwordx4 v[150:151], off
	s_mov_b32 m0, s33
	s_nop 0
	global_load_lds_dwordx4 v[152:153], off
	s_waitcnt vmcnt(8)
	s_waitcnt lgkmcnt(0)
	s_barrier
	s_waitcnt lgkmcnt(0)
	v_mfma_f32_16x16x32_bf16 v[60:63], v[138:141], v[182:185], v[60:63]
	v_mfma_f32_16x16x32_bf16 v[56:59], v[158:161], v[182:185], v[56:59]
	v_mfma_f32_16x16x32_bf16 v[44:47], v[138:141], v[190:193], v[44:47]
	v_mfma_f32_16x16x32_bf16 v[40:43], v[158:161], v[190:193], v[40:43]
	v_mfma_f32_16x16x32_bf16 v[28:31], v[138:141], v[198:201], v[28:31]
	v_mfma_f32_16x16x32_bf16 v[24:27], v[158:161], v[198:201], v[24:27]
	v_mfma_f32_16x16x32_bf16 v[12:15], v[138:141], v[212:215], v[12:15]
	v_mfma_f32_16x16x32_bf16 v[8:11], v[158:161], v[212:215], v[8:11]
	v_mfma_f32_16x16x32_bf16 v[60:63], v[154:157], v[186:189], v[60:63]
	v_mfma_f32_16x16x32_bf16 v[56:59], v[162:165], v[186:189], v[56:59]
	v_mfma_f32_16x16x32_bf16 v[44:47], v[154:157], v[194:197], v[44:47]
	v_mfma_f32_16x16x32_bf16 v[40:43], v[162:165], v[194:197], v[40:43]
	v_mfma_f32_16x16x32_bf16 v[28:31], v[154:157], v[202:205], v[28:31]
	v_mfma_f32_16x16x32_bf16 v[24:27], v[162:165], v[202:205], v[24:27]
	v_mfma_f32_16x16x32_bf16 v[12:15], v[154:157], v[220:223], v[12:15]
	v_mfma_f32_16x16x32_bf16 v[8:11], v[162:165], v[220:223], v[8:11]
	v_mfma_f32_16x16x32_bf16 v[52:55], v[166:169], v[182:185], v[52:55]
	v_mfma_f32_16x16x32_bf16 v[48:51], v[174:177], v[182:185], v[48:51]
	v_mfma_f32_16x16x32_bf16 v[36:39], v[166:169], v[190:193], v[36:39]
	v_mfma_f32_16x16x32_bf16 v[32:35], v[174:177], v[190:193], v[32:35]
	v_mfma_f32_16x16x32_bf16 v[20:23], v[166:169], v[198:201], v[20:23]
	v_mfma_f32_16x16x32_bf16 v[16:19], v[174:177], v[198:201], v[16:19]
	v_mfma_f32_16x16x32_bf16 v[4:7], v[166:169], v[212:215], v[4:7]
	v_mfma_f32_16x16x32_bf16 v[0:3], v[174:177], v[212:215], v[0:3]
	v_mfma_f32_16x16x32_bf16 v[52:55], v[170:173], v[186:189], v[52:55]
	v_mfma_f32_16x16x32_bf16 v[48:51], v[178:181], v[186:189], v[48:51]
	v_mfma_f32_16x16x32_bf16 v[36:39], v[170:173], v[194:197], v[36:39]
	v_mfma_f32_16x16x32_bf16 v[32:35], v[178:181], v[194:197], v[32:35]
	v_mfma_f32_16x16x32_bf16 v[20:23], v[170:173], v[202:205], v[20:23]
	v_mfma_f32_16x16x32_bf16 v[16:19], v[178:181], v[202:205], v[16:19]
	v_mfma_f32_16x16x32_bf16 v[4:7], v[170:173], v[220:223], v[4:7]
	v_mfma_f32_16x16x32_bf16 v[0:3], v[178:181], v[220:223], v[0:3]
	s_barrier
	s_add_i32 s49, 0, 0x18000
	s_add_i32 s50, 0, 0x1c000
	v_add_u32_e32 v162, s49, v144
	v_add_u32_e32 v178, s50, v144
	ds_read_b128 v[138:141], v162
	ds_read_b128 v[154:157], v162 offset:1024
	ds_read_b128 v[158:161], v162 offset:2048
	ds_read_b128 v[162:165], v162 offset:3072
	ds_read_b128 v[166:169], v178
	ds_read_b128 v[170:173], v178 offset:1024
	ds_read_b128 v[174:177], v178 offset:2048
	ds_read_b128 v[178:181], v178 offset:3072
	s_add_u32 s22, s22, 0x40000
	s_addc_u32 s23, s23, 0
	s_mov_b32 m0, s34
	ds_read_b128 v[182:185], v145 offset:32768
	ds_read_b128 v[186:189], v145 offset:33792
	ds_read_b128 v[190:193], v145 offset:34816
	ds_read_b128 v[194:197], v145 offset:35840
	ds_read_b128 v[198:201], v145 offset:36864
	ds_read_b128 v[202:205], v145 offset:37888
	ds_read_b128 v[212:215], v145 offset:38912
	ds_read_b128 v[220:223], v145 offset:39936
	global_load_lds_dwordx4 v132, s[22:23]
	s_mov_b32 m0, s35
	s_nop 0
	global_load_lds_dwordx4 v130, s[22:23]
	s_waitcnt vmcnt(8)
	s_waitcnt lgkmcnt(0)
	s_barrier
	s_waitcnt lgkmcnt(0)
	v_mfma_f32_16x16x32_bf16 v[124:127], v[138:141], v[182:185], v[124:127]
	v_mfma_f32_16x16x32_bf16 v[120:123], v[158:161], v[182:185], v[120:123]
	v_mfma_f32_16x16x32_bf16 v[108:111], v[138:141], v[190:193], v[108:111]
	v_mfma_f32_16x16x32_bf16 v[104:107], v[158:161], v[190:193], v[104:107]
	v_mfma_f32_16x16x32_bf16 v[92:95], v[138:141], v[198:201], v[92:95]
	v_mfma_f32_16x16x32_bf16 v[88:91], v[158:161], v[198:201], v[88:91]
	v_mfma_f32_16x16x32_bf16 v[76:79], v[138:141], v[212:215], v[76:79]
	v_mfma_f32_16x16x32_bf16 v[72:75], v[158:161], v[212:215], v[72:75]
	v_mfma_f32_16x16x32_bf16 v[124:127], v[154:157], v[186:189], v[124:127]
	v_mfma_f32_16x16x32_bf16 v[120:123], v[162:165], v[186:189], v[120:123]
	v_mfma_f32_16x16x32_bf16 v[108:111], v[154:157], v[194:197], v[108:111]
	v_mfma_f32_16x16x32_bf16 v[104:107], v[162:165], v[194:197], v[104:107]
	v_mfma_f32_16x16x32_bf16 v[92:95], v[154:157], v[202:205], v[92:95]
	v_mfma_f32_16x16x32_bf16 v[88:91], v[162:165], v[202:205], v[88:91]
	v_mfma_f32_16x16x32_bf16 v[76:79], v[154:157], v[220:223], v[76:79]
	v_mfma_f32_16x16x32_bf16 v[72:75], v[162:165], v[220:223], v[72:75]
	v_mfma_f32_16x16x32_bf16 v[116:119], v[166:169], v[182:185], v[116:119]
	v_mfma_f32_16x16x32_bf16 v[112:115], v[174:177], v[182:185], v[112:115]
	v_mfma_f32_16x16x32_bf16 v[100:103], v[166:169], v[190:193], v[100:103]
	v_mfma_f32_16x16x32_bf16 v[96:99], v[174:177], v[190:193], v[96:99]
	v_mfma_f32_16x16x32_bf16 v[84:87], v[166:169], v[198:201], v[84:87]
	v_mfma_f32_16x16x32_bf16 v[80:83], v[174:177], v[198:201], v[80:83]
	v_mfma_f32_16x16x32_bf16 v[68:71], v[166:169], v[212:215], v[68:71]
	v_mfma_f32_16x16x32_bf16 v[64:67], v[174:177], v[212:215], v[64:67]
	v_mfma_f32_16x16x32_bf16 v[116:119], v[170:173], v[186:189], v[116:119]
	v_mfma_f32_16x16x32_bf16 v[112:115], v[178:181], v[186:189], v[112:115]
	v_mfma_f32_16x16x32_bf16 v[100:103], v[170:173], v[194:197], v[100:103]
	v_mfma_f32_16x16x32_bf16 v[96:99], v[178:181], v[194:197], v[96:99]
	v_mfma_f32_16x16x32_bf16 v[84:87], v[170:173], v[202:205], v[84:87]
	v_mfma_f32_16x16x32_bf16 v[80:83], v[178:181], v[202:205], v[80:83]
	v_mfma_f32_16x16x32_bf16 v[68:71], v[170:173], v[220:223], v[68:71]
	v_mfma_f32_16x16x32_bf16 v[64:67], v[178:181], v[220:223], v[64:67]
	s_barrier
	s_add_i32 s22, s49, s30
	v_lshl_add_u64 v[142:143], v[142:143], 0, s[28:29]
	s_mov_b32 m0, s22
	ds_read_b128 v[182:185], v145 offset:49152
	ds_read_b128 v[186:189], v145 offset:50176
	ds_read_b128 v[190:193], v145 offset:51200
	ds_read_b128 v[194:197], v145 offset:52224
	ds_read_b128 v[198:201], v145 offset:53248
	ds_read_b128 v[202:205], v145 offset:54272
	ds_read_b128 v[212:215], v145 offset:55296
	ds_read_b128 v[220:223], v145 offset:56320
	global_load_lds_dwordx4 v[142:143], off
	s_add_i32 m0, s22, 0x2000
	s_add_u32 s20, s20, 0x40080
	v_lshl_add_u64 v[142:143], v[146:147], 0, s[28:29]
	s_addc_u32 s21, s21, 0
	s_add_i32 s22, s50, s30
	global_load_lds_dwordx4 v[142:143], off
	s_mov_b32 m0, s22
	s_nop 0
	global_load_lds_dwordx4 v148, s[20:21]
	s_add_i32 m0, s22, 0x2000
	s_nop 0
	global_load_lds_dwordx4 v128, s[20:21]
	v_lshl_add_u64 v[142:143], v[150:151], 0, s[28:29]
	s_mov_b32 m0, s39
	s_nop 0
	global_load_lds_dwordx4 v[142:143], off
	v_lshl_add_u64 v[142:143], v[152:153], 0, s[28:29]
	s_mov_b32 m0, s40
	s_nop 0
	global_load_lds_dwordx4 v[142:143], off
	s_waitcnt vmcnt(8)
	s_waitcnt lgkmcnt(0)
	s_barrier
	s_waitcnt lgkmcnt(0)
	v_mfma_f32_16x16x32_bf16 v[60:63], v[138:141], v[182:185], v[60:63]
	v_mfma_f32_16x16x32_bf16 v[56:59], v[158:161], v[182:185], v[56:59]
	v_mfma_f32_16x16x32_bf16 v[44:47], v[138:141], v[190:193], v[44:47]
	v_mfma_f32_16x16x32_bf16 v[40:43], v[158:161], v[190:193], v[40:43]
	v_mfma_f32_16x16x32_bf16 v[28:31], v[138:141], v[198:201], v[28:31]
	v_mfma_f32_16x16x32_bf16 v[24:27], v[158:161], v[198:201], v[24:27]
	v_mfma_f32_16x16x32_bf16 v[12:15], v[138:141], v[212:215], v[12:15]
	v_mfma_f32_16x16x32_bf16 v[8:11], v[158:161], v[212:215], v[8:11]
	v_mfma_f32_16x16x32_bf16 v[60:63], v[154:157], v[186:189], v[60:63]
	v_mfma_f32_16x16x32_bf16 v[56:59], v[162:165], v[186:189], v[56:59]
	v_mfma_f32_16x16x32_bf16 v[44:47], v[154:157], v[194:197], v[44:47]
	v_mfma_f32_16x16x32_bf16 v[40:43], v[162:165], v[194:197], v[40:43]
	v_mfma_f32_16x16x32_bf16 v[28:31], v[154:157], v[202:205], v[28:31]
	v_mfma_f32_16x16x32_bf16 v[24:27], v[162:165], v[202:205], v[24:27]
	v_mfma_f32_16x16x32_bf16 v[12:15], v[154:157], v[220:223], v[12:15]
	v_mfma_f32_16x16x32_bf16 v[8:11], v[162:165], v[220:223], v[8:11]
	v_mfma_f32_16x16x32_bf16 v[52:55], v[166:169], v[182:185], v[52:55]
	v_mfma_f32_16x16x32_bf16 v[48:51], v[174:177], v[182:185], v[48:51]
	v_mfma_f32_16x16x32_bf16 v[36:39], v[166:169], v[190:193], v[36:39]
	v_mfma_f32_16x16x32_bf16 v[32:35], v[174:177], v[190:193], v[32:35]
	v_mfma_f32_16x16x32_bf16 v[20:23], v[166:169], v[198:201], v[20:23]
	v_mfma_f32_16x16x32_bf16 v[16:19], v[174:177], v[198:201], v[16:19]
	v_mfma_f32_16x16x32_bf16 v[4:7], v[166:169], v[212:215], v[4:7]
	v_mfma_f32_16x16x32_bf16 v[0:3], v[174:177], v[212:215], v[0:3]
	v_mfma_f32_16x16x32_bf16 v[52:55], v[170:173], v[186:189], v[52:55]
	v_mfma_f32_16x16x32_bf16 v[48:51], v[178:181], v[186:189], v[48:51]
	v_mfma_f32_16x16x32_bf16 v[36:39], v[170:173], v[194:197], v[36:39]
	v_mfma_f32_16x16x32_bf16 v[32:35], v[178:181], v[194:197], v[32:35]
	v_mfma_f32_16x16x32_bf16 v[20:23], v[170:173], v[202:205], v[20:23]
	v_mfma_f32_16x16x32_bf16 v[16:19], v[178:181], v[202:205], v[16:19]
	v_mfma_f32_16x16x32_bf16 v[4:7], v[170:173], v[220:223], v[4:7]
	v_mfma_f32_16x16x32_bf16 v[0:3], v[178:181], v[220:223], v[0:3]
	s_barrier
	s_add_i32 s48, s48, 2
	s_add_u32 s18, s18, 0x100
	s_addc_u32 s19, s19, 0
	s_add_u32 s46, s46, 0x100
	s_addc_u32 s47, s47, 0
	s_cmp_gt_u32 s48, 13
	s_cbranch_scc0 .LBB0_1438
	s_and_b64 vcc, exec, s[8:9]
	s_cbranch_vccz .LBB0_1441
	s_barrier
